# LRU: dir-1 gate-weight fragment loads issued at the start of dir-0 VALU section (4 fragments copied into place) on top of the dir-0 hoist
# speedup vs baseline: 1.0036x; 1.0036x over previous
; DI unsigned cvtpk(float lo, float hi) { unsigned r; asm volatile("v_cvt_pk_bf16_f32 %0, %1, %2" : "=v"(r) : "v"(lo), "v"(hi)); return r; }
; DI void lru_tile(const Params& p, unsigned char* shm, int c, int nb, const LruPar par) {
;     ...
;         for (int o = 0; o < 4; ++o) { float u8[8];
; #pragma unroll
;             for (int i = 0; i < 8; ++i) { float a = bias[i];
; #pragma unroll
;                 for (int tp = 0; tp < 4; ++tp) a += xr[o + tp][i] * w[tp][i];
;                 u8[i] = a; }
;             *(u32x4*)(UB + (rg * 4 + o) * LDU + cgp * 8) = (u32x4){cvtpk(u8[0], u8[1]), cvtpk(u8[2], u8[3]), cvtpk(u8[4], u8[5]), cvtpk(u8[6], u8[7])};
;         }
;     ...
;         for (int s = 0; s < 4; ++s)
; #pragma unroll
;             for (int gt = 0; gt < 2; ++gt) bfr[s][gt] = *(const bf16x8*)(LWT + ((size_t)((d * 2 + gt) * 16 + nb) * 128 + chl) * 128 + s * 32 + q * 8);
.LBB0_228:
	s_or_b64 exec, exec, s[4:5]
	s_waitcnt vmcnt(0)
	v_and_b32_e32 v240, 0x3c0, v202
	v_lshrrev_b32_e32 v240, 2, v240
	v_and_or_b32 v240, v202, 15, v240
	v_add_u32_e32 v240, s38, v240
	v_bfe_u32 v241, v202, 4, 2
	v_lshlrev_b32_e32 v240, 8, v240
	v_lshl_add_u32 v240, v241, 4, v240
	s_add_u32 s72, s34, 0x80000
	s_addc_u32 s73, s35, 0
	global_load_dwordx4 v[208:211], v240, s[34:35]
	global_load_dwordx4 v[216:219], v240, s[34:35] offset:64
	global_load_dwordx4 v[212:215], v240, s[72:73]
	global_load_dwordx4 v[220:223], v240, s[72:73] offset:64
	global_load_dwordx4 v[224:227], v240, s[34:35] offset:128
	global_load_dwordx4 v[232:235], v240, s[34:35] offset:192
	global_load_dwordx4 v[228:231], v240, s[72:73] offset:128
	global_load_dwordx4 v[236:239], v240, s[72:73] offset:192
	v_lshlrev_b32_e32 v109, 16, v61
	v_and_b32_e32 v105, 0xffff0000, v61
	v_lshlrev_b32_e32 v97, 16, v63
	v_and_b32_e32 v61, 0xffff0000, v63
	v_lshlrev_b32_e32 v115, 16, v57
	v_and_b32_e32 v111, 0xffff0000, v57
	v_lshlrev_b32_e32 v107, 16, v58
	v_and_b32_e32 v103, 0xffff0000, v58
	v_lshlrev_b32_e32 v63, 16, v59
	v_and_b32_e32 v57, 0xffff0000, v59
	v_lshlrev_b32_e32 v133, 16, v53
	v_and_b32_e32 v131, 0xffff0000, v53
	v_lshlrev_b32_e32 v125, 16, v55
	v_and_b32_e32 v59, 0xffff0000, v55
	v_lshlrev_b32_e32 v124, 16, v51
	v_and_b32_e32 v58, 0xffff0000, v51
	v_lshlrev_b32_e32 v139, 16, v44
	v_lshlrev_b32_e32 v138, 16, v40
	v_lshlrev_b32_e32 v123, 16, v64
	v_and_b32_e32 v55, 0xffff0000, v64
	v_lshlrev_b32_e32 v53, 16, v65
	v_and_b32_e32 v51, 0xffff0000, v65
	v_mov_b32_e32 v64, v36
	v_mov_b32_e32 v65, v12
	v_lshlrev_b32_e32 v132, 16, v49
	v_and_b32_e32 v130, 0xffff0000, v49
	v_lshlrev_b32_e32 v143, 16, v45
	v_and_b32_e32 v145, 0xffff0000, v45
	v_lshlrev_b32_e32 v151, 16, v47
	v_and_b32_e32 v153, 0xffff0000, v47
	v_lshlrev_b32_e32 v150, 16, v43
	v_and_b32_e32 v152, 0xffff0000, v43
	v_lshlrev_b32_e32 v49, 16, v66
	v_and_b32_e32 v47, 0xffff0000, v66
	v_lshlrev_b32_e32 v45, 16, v67
	v_and_b32_e32 v43, 0xffff0000, v67
	v_pk_mul_f32 v[66:67], v[64:65], v[138:139]
	v_lshlrev_b32_e32 v137, 16, v52
	v_add_f32_e32 v12, v20, v66
	v_lshlrev_b32_e32 v136, 16, v48
	v_add_f32_e32 v12, v12, v67
	v_mov_b32_e32 v66, v32
	v_mov_b32_e32 v67, v16
	v_pk_mul_f32 v[154:155], v[66:67], v[136:137]
	v_and_b32_e32 v141, 0xffff0000, v44
	v_add_f32_e32 v12, v12, v154
	v_and_b32_e32 v140, 0xffff0000, v40
	v_lshlrev_b32_e32 v142, 16, v41
	v_and_b32_e32 v144, 0xffff0000, v41
	v_add_f32_e32 v41, v12, v155
	v_mov_b32_e32 v12, v37
	v_pk_mul_f32 v[36:37], v[12:13], v[140:141]
	v_and_b32_e32 v135, 0xffff0000, v52
	v_add_f32_e32 v16, v21, v36
	v_and_b32_e32 v134, 0xffff0000, v48
	v_add_f32_e32 v36, v16, v37
	v_mov_b32_e32 v16, v33
	v_pk_mul_f32 v[32:33], v[16:17], v[134:135]
	v_lshlrev_b32_e32 v146, 16, v42
	v_add_f32_e32 v32, v36, v32
	v_and_b32_e32 v148, 0xffff0000, v42
	v_add_f32_e32 v42, v32, v33
	v_mov_b32_e32 v32, v38
	v_mov_b32_e32 v33, v14
	v_pk_mul_f32 v[36:37], v[32:33], v[142:143]
	v_lshlrev_b32_e32 v147, 16, v46
	v_add_f32_e32 v14, v22, v36
	v_add_f32_e32 v14, v14, v37
	v_mov_b32_e32 v36, v34
	v_mov_b32_e32 v37, v18
	v_pk_mul_f32 v[154:155], v[36:37], v[132:133]
	v_and_b32_e32 v149, 0xffff0000, v46
	v_add_f32_e32 v14, v14, v154
	v_add_f32_e32 v44, v14, v155
	v_mov_b32_e32 v14, v39
	v_pk_mul_f32 v[38:39], v[14:15], v[144:145]
	v_lshlrev_b32_e32 v129, 16, v54
	v_add_f32_e32 v18, v23, v38
	v_add_f32_e32 v38, v18, v39
	v_mov_b32_e32 v18, v35
	v_pk_mul_f32 v[34:35], v[18:19], v[130:131]
	v_lshlrev_b32_e32 v128, 16, v50
	v_add_f32_e32 v34, v38, v34
	v_add_f32_e32 v46, v34, v35
	v_mov_b32_e32 v34, v28
	v_mov_b32_e32 v35, v0
	v_pk_mul_f32 v[38:39], v[34:35], v[146:147]
	v_and_b32_e32 v127, 0xffff0000, v54
	v_add_f32_e32 v0, v8, v38
	v_add_f32_e32 v0, v0, v39
	v_mov_b32_e32 v38, v24
	v_mov_b32_e32 v39, v4
	v_pk_mul_f32 v[154:155], v[38:39], v[128:129]
	v_and_b32_e32 v126, 0xffff0000, v50
	v_add_f32_e32 v0, v0, v154
	v_add_f32_e32 v48, v0, v155
	v_mov_b32_e32 v0, v29
	v_pk_mul_f32 v[28:29], v[0:1], v[148:149]
	v_mov_b32_e32 v154, v26
	v_add_f32_e32 v4, v9, v28
	v_add_f32_e32 v28, v4, v29
	v_mov_b32_e32 v4, v25
	v_pk_mul_f32 v[24:25], v[4:5], v[126:127]
	v_mov_b32_e32 v29, v2
	v_add_f32_e32 v24, v28, v24
	v_mov_b32_e32 v28, v30
	v_add_f32_e32 v50, v24, v25
	v_pk_mul_f32 v[24:25], v[28:29], v[150:151]
	v_mov_b32_e32 v155, v6
	v_add_f32_e32 v2, v10, v24
	v_add_f32_e32 v2, v2, v25
	v_pk_mul_f32 v[24:25], v[154:155], v[124:125]
	v_lshl_add_u32 v40, v98, 1, 0
	v_add_f32_e32 v2, v2, v24
	v_add_f32_e32 v30, v2, v25
	v_mov_b32_e32 v2, v31
	v_pk_mul_f32 v[24:25], v[2:3], v[152:153]
	s_ashr_i32 s4, s6, 6
	v_add_f32_e32 v6, v11, v24
	v_add_f32_e32 v26, v6, v25
	v_mov_b32_e32 v6, v27
	v_pk_mul_f32 v[24:25], v[6:7], v[58:59]
	v_lshlrev_b32_e32 v121, 16, v56
	v_add_f32_e32 v24, v26, v24
	v_add_f32_e32 v27, v24, v25
	v_cvt_pk_bf16_f32 v24, v41, v42
	v_cvt_pk_bf16_f32 v25, v44, v46
	v_cvt_pk_bf16_f32 v26, v48, v50
	v_cvt_pk_bf16_f32 v27, v30, v27
	v_mad_u64_u32 v[30:31], s[6:7], v95, s67, v[40:41]
	ds_write_b128 v30, v[24:27]
	v_mov_b32_e32 v24, v139
	v_mov_b32_e32 v25, v136
	v_pk_mul_f32 v[24:25], v[64:65], v[24:25]
	v_mov_b32_e32 v120, v137
	v_add_f32_e32 v24, v20, v24
	v_add_f32_e32 v26, v24, v25
	v_pk_mul_f32 v[24:25], v[66:67], v[120:121]
	v_and_b32_e32 v119, 0xffff0000, v56
	v_add_f32_e32 v24, v26, v24
	v_add_f32_e32 v26, v24, v25
	v_mov_b32_e32 v24, v141
	v_mov_b32_e32 v25, v134
	v_pk_mul_f32 v[24:25], v[12:13], v[24:25]
	v_mov_b32_e32 v118, v135
	v_add_f32_e32 v24, v21, v24
	v_add_f32_e32 v27, v24, v25
	v_pk_mul_f32 v[24:25], v[16:17], v[118:119]
	v_mov_b32_e32 v114, v133
	v_add_f32_e32 v24, v27, v24
	v_add_f32_e32 v27, v24, v25
; DI unsigned cvtpk(float lo, float hi) { unsigned r; asm volatile("v_cvt_pk_bf16_f32 %0, %1, %2" : "=v"(r) : "v"(lo), "v"(hi)); return r; }
; DI void lru_tile(const Params& p, unsigned char* shm, int c, int nb, const LruPar par) {
;     ...
;         for (int o = 0; o < 4; ++o) { float u8[8];
; #pragma unroll
;             for (int i = 0; i < 8; ++i) { float a = bias[i];
; #pragma unroll
;                 for (int tp = 0; tp < 4; ++tp) a += xr[o + tp][i] * w[tp][i];
;                 u8[i] = a; }
;             *(u32x4*)(UB + (rg * 4 + o) * LDU + cgp * 8) = (u32x4){cvtpk(u8[0], u8[1]), cvtpk(u8[2], u8[3]), cvtpk(u8[4], u8[5]), cvtpk(u8[6], u8[7])};
;         }
;     }
;     __syncthreads();
	v_mov_b32_e32 v24, v143
	v_mov_b32_e32 v25, v132
	v_pk_mul_f32 v[24:25], v[32:33], v[24:25]
	v_mov_b32_e32 v110, v131
	v_add_f32_e32 v24, v22, v24
	v_add_f32_e32 v31, v24, v25
	v_pk_mul_f32 v[24:25], v[36:37], v[114:115]
	v_mov_b32_e32 v106, v129
	v_add_f32_e32 v24, v31, v24
	v_add_f32_e32 v31, v24, v25
	v_mov_b32_e32 v24, v145
	v_mov_b32_e32 v25, v130
	v_pk_mul_f32 v[24:25], v[14:15], v[24:25]
	v_mov_b32_e32 v102, v127
	v_add_f32_e32 v24, v23, v24
	v_add_f32_e32 v41, v24, v25
	v_pk_mul_f32 v[24:25], v[18:19], v[110:111]
	v_lshlrev_b32_e32 v101, 16, v62
	v_add_f32_e32 v24, v41, v24
	v_add_f32_e32 v41, v24, v25
	v_mov_b32_e32 v24, v147
	v_mov_b32_e32 v25, v128
	v_pk_mul_f32 v[24:25], v[34:35], v[24:25]
	v_and_b32_e32 v99, 0xffff0000, v62
	v_add_f32_e32 v24, v8, v24
	v_add_f32_e32 v42, v24, v25
	v_pk_mul_f32 v[24:25], v[38:39], v[106:107]
	v_mov_b32_e32 v62, v125
	v_add_f32_e32 v24, v42, v24
	v_add_f32_e32 v42, v24, v25
	v_mov_b32_e32 v24, v149
	v_mov_b32_e32 v25, v126
	v_pk_mul_f32 v[24:25], v[0:1], v[24:25]
	v_mov_b32_e32 v56, v59
	v_add_f32_e32 v24, v9, v24
	v_add_f32_e32 v44, v24, v25
	v_pk_mul_f32 v[24:25], v[4:5], v[102:103]
	v_lshlrev_b32_e32 v117, 16, v60
	v_add_f32_e32 v24, v44, v24
	v_add_f32_e32 v44, v24, v25
	v_mov_b32_e32 v24, v151
	v_mov_b32_e32 v25, v124
	v_pk_mul_f32 v[24:25], v[28:29], v[24:25]
	v_mov_b32_e32 v116, v121
	v_add_f32_e32 v24, v10, v24
	v_add_f32_e32 v46, v24, v25
	v_pk_mul_f32 v[24:25], v[154:155], v[62:63]
	v_and_b32_e32 v113, 0xffff0000, v60
	v_add_f32_e32 v24, v46, v24
	v_add_f32_e32 v46, v24, v25
	v_mov_b32_e32 v24, v153
	v_mov_b32_e32 v25, v58
	v_pk_mul_f32 v[24:25], v[2:3], v[24:25]
	v_mov_b32_e32 v112, v119
	v_add_f32_e32 v24, v11, v24
	v_add_f32_e32 v48, v24, v25
	v_pk_mul_f32 v[24:25], v[6:7], v[56:57]
	v_mov_b32_e32 v108, v115
	v_add_f32_e32 v24, v48, v24
	v_add_f32_e32 v48, v24, v25
	v_cvt_pk_bf16_f32 v24, v26, v27
	v_cvt_pk_bf16_f32 v25, v31, v41
	v_cvt_pk_bf16_f32 v26, v42, v44
	v_cvt_pk_bf16_f32 v27, v46, v48
	ds_write_b128 v30, v[24:27] offset:272
	v_pk_mul_f32 v[24:25], v[64:65], v[136:137]
	v_mov_b32_e32 v104, v111
	v_add_f32_e32 v24, v20, v24
	v_add_f32_e32 v26, v24, v25
	v_pk_mul_f32 v[24:25], v[66:67], v[116:117]
	v_mov_b32_e32 v100, v107
	v_add_f32_e32 v24, v26, v24
	v_add_f32_e32 v26, v24, v25
	v_pk_mul_f32 v[24:25], v[12:13], v[134:135]
	v_mov_b32_e32 v98, v103
	v_add_f32_e32 v24, v21, v24
	v_add_f32_e32 v27, v24, v25
	v_pk_mul_f32 v[24:25], v[16:17], v[112:113]
	v_mov_b32_e32 v96, v63
	v_add_f32_e32 v24, v27, v24
	v_add_f32_e32 v27, v24, v25
	v_pk_mul_f32 v[24:25], v[32:33], v[132:133]
	v_pk_mul_f32 v[12:13], v[12:13], v[118:119]
	v_add_f32_e32 v24, v22, v24
	v_add_f32_e32 v31, v24, v25
	v_pk_mul_f32 v[24:25], v[36:37], v[108:109]
	v_add_f32_e32 v12, v21, v12
	v_add_f32_e32 v24, v31, v24
	v_add_f32_e32 v31, v24, v25
	v_pk_mul_f32 v[24:25], v[14:15], v[130:131]
	v_mov_b32_e32 v54, v113
	v_add_f32_e32 v24, v23, v24
	v_add_f32_e32 v41, v24, v25
	v_pk_mul_f32 v[24:25], v[18:19], v[104:105]
	v_mov_b32_e32 v60, v57
	v_add_f32_e32 v24, v41, v24
	v_add_f32_e32 v41, v24, v25
	v_pk_mul_f32 v[24:25], v[34:35], v[128:129]
	v_add_f32_e32 v21, v12, v13
	v_add_f32_e32 v24, v8, v24
	v_add_f32_e32 v42, v24, v25
	v_pk_mul_f32 v[24:25], v[38:39], v[100:101]
	v_pk_mul_f32 v[12:13], v[16:17], v[54:55]
	v_add_f32_e32 v24, v42, v24
	v_add_f32_e32 v42, v24, v25
	v_pk_mul_f32 v[24:25], v[0:1], v[126:127]
	v_add_f32_e32 v12, v21, v12
	v_add_f32_e32 v24, v9, v24
	v_add_f32_e32 v44, v24, v25
	v_pk_mul_f32 v[24:25], v[4:5], v[98:99]
	v_add_f32_e32 v16, v12, v13
	v_add_f32_e32 v24, v44, v24
	v_add_f32_e32 v44, v24, v25
	v_pk_mul_f32 v[24:25], v[28:29], v[124:125]
	v_pk_mul_f32 v[12:13], v[32:33], v[114:115]
	v_add_f32_e32 v24, v10, v24
	v_add_f32_e32 v46, v24, v25
	v_pk_mul_f32 v[24:25], v[154:155], v[96:97]
	v_pk_mul_f32 v[0:1], v[0:1], v[102:103]
	v_add_f32_e32 v24, v46, v24
	v_add_f32_e32 v46, v24, v25
	v_pk_mul_f32 v[24:25], v[2:3], v[58:59]
	v_add_f32_e32 v12, v22, v12
	v_add_f32_e32 v24, v11, v24
	v_add_f32_e32 v48, v24, v25
	v_pk_mul_f32 v[24:25], v[6:7], v[60:61]
	v_mov_b32_e32 v52, v109
	v_add_f32_e32 v24, v48, v24
	v_add_f32_e32 v48, v24, v25
	v_cvt_pk_bf16_f32 v24, v26, v27
	v_cvt_pk_bf16_f32 v25, v31, v41
	v_cvt_pk_bf16_f32 v26, v42, v44
	v_cvt_pk_bf16_f32 v27, v46, v48
	v_add_f32_e32 v0, v9, v0
	v_mov_b32_e32 v46, v99
	v_add_f32_e32 v17, v12, v13
	v_pk_mul_f32 v[12:13], v[36:37], v[52:53]
	v_add_f32_e32 v9, v0, v1
	v_pk_mul_f32 v[0:1], v[4:5], v[46:47]
	v_add_f32_e32 v12, v17, v12
	v_add_f32_e32 v0, v9, v0
	v_add_f32_e32 v17, v12, v13
	v_pk_mul_f32 v[12:13], v[14:15], v[110:111]
	v_add_f32_e32 v4, v0, v1
	v_pk_mul_f32 v[0:1], v[28:29], v[62:63]
	v_add_f32_e32 v12, v23, v12
	v_mov_b32_e32 v50, v105
	v_add_f32_e32 v0, v10, v0
	v_mov_b32_e32 v44, v97
	v_add_f32_e32 v14, v12, v13
	v_pk_mul_f32 v[12:13], v[18:19], v[50:51]
	v_add_f32_e32 v5, v0, v1
	v_pk_mul_f32 v[0:1], v[154:155], v[44:45]
	v_add_f32_e32 v12, v14, v12
	v_add_f32_e32 v0, v5, v0
	ds_write_b128 v30, v[24:27] offset:544
	v_pk_mul_f32 v[24:25], v[64:65], v[120:121]
	v_add_f32_e32 v14, v12, v13
	v_pk_mul_f32 v[12:13], v[34:35], v[106:107]
	v_add_f32_e32 v5, v0, v1
	v_pk_mul_f32 v[0:1], v[2:3], v[56:57]
	v_add_f32_e32 v20, v20, v24
	v_mov_b32_e32 v122, v117
	v_add_f32_e32 v8, v8, v12
	v_mov_b32_e32 v48, v101
	v_add_f32_e32 v0, v11, v0
	v_mov_b32_e32 v42, v61
	v_add_f32_e32 v20, v20, v25
	v_pk_mul_f32 v[24:25], v[66:67], v[122:123]
	v_add_f32_e32 v8, v8, v13
	v_pk_mul_f32 v[12:13], v[38:39], v[48:49]
	v_add_f32_e32 v2, v0, v1
	v_pk_mul_f32 v[0:1], v[6:7], v[42:43]
	v_and_b32_e32 v164, 15, v75
	v_add_f32_e32 v20, v20, v24
	v_add_f32_e32 v8, v8, v12
	v_add_f32_e32 v0, v2, v0
	v_lshl_or_b32 v48, s4, 4, v164
	s_lshl_b32 s4, s4, 12
	s_ashr_i32 s59, s58, 31
	v_add_f32_e32 v20, v20, v25
	v_add_f32_e32 v8, v8, v13
	v_add_f32_e32 v3, v0, v1
	v_cvt_pk_bf16_f32 v0, v20, v16
	v_cvt_pk_bf16_f32 v1, v17, v14
	v_cvt_pk_bf16_f32 v2, v8, v4
	v_or_b32_e32 v4, 3, v94
	s_add_i32 s8, s4, 0
	s_lshl_b64 s[4:5], s[58:59], 14
	v_cvt_pk_bf16_f32 v3, v5, v3
	v_mad_u64_u32 v[4:5], s[6:7], v4, s67, v[40:41]
	v_bfe_u32 v99, v75, 4, 2
	v_ashrrev_i32_e32 v49, 31, v48
	s_add_u32 s4, s37, s4
	ds_write_b128 v4, v[0:3]
	v_lshlrev_b32_e32 v68, 4, v99
	v_lshl_add_u64 v[0:1], v[48:49], 0, s[38:39]
	s_addc_u32 s5, s41, s5
	s_or_b32 s6, s38, 0x800
	s_mov_b32 s7, s39
	v_lshl_add_u64 v[160:161], s[34:35], 0, v[68:69]
	v_lshlrev_b64 v[0:1], 8, v[0:1]
	v_lshl_add_u64 v[8:9], v[48:49], 0, s[6:7]
	v_lshl_add_u64 v[66:67], v[160:161], 0, v[0:1]
	v_add_u32_e32 v165, 0, v68
	v_lshlrev_b64 v[8:9], 8, v[8:9]
	s_waitcnt lgkmcnt(0)
	s_barrier
; DI void lru_tile(const Params& p, unsigned char* shm, int c, int nb, const LruPar par) {
;     ...
;         for (int s = 0; s < 4; ++s)
; #pragma unroll
;             for (int gt = 0; gt < 2; ++gt) bfr[s][gt] = *(const bf16x8*)(LWT + ((size_t)((d * 2 + gt) * 16 + nb) * 128 + chl) * 128 + s * 32 + q * 8);
; #pragma unroll
;         for (int s = 0; s < 4; ++s) {
; #pragma unroll
;             for (int rt = 0; rt < 8; ++rt) {
;                 const bf16x8 af = *(const bf16x8*)(UB + (rt * 16 + col) * LDU + s * 32 + q * 8);
; #pragma unroll
;                 for (int gt = 0; gt < 2; ++gt) acc[gt][rt] = __builtin_amdgcn_mfma_f32_16x16x32_bf16(af, bfr[s][gt], acc[gt][rt], 0, 0, 0);
;             }
;             __builtin_amdgcn_sched_barrier(0);
;         }
	v_mad_u32_u24 v68, v164, s67, v165
	v_lshl_add_u64 v[96:97], v[160:161], 0, v[8:9]
	ds_read_b128 v[4:7], v68
	ds_read_b128 v[12:15], v68 offset:4352
	ds_read_b128 v[32:35], v68 offset:8704
	ds_read_b128 v[36:39], v68 offset:13056
	ds_read_b128 v[50:53], v68 offset:17408
	ds_read_b128 v[54:57], v68 offset:21760
	ds_read_b128 v[58:61], v68 offset:26112
	ds_read_b128 v[116:119], v68 offset:30464
	s_waitcnt vmcnt(7) lgkmcnt(7)
	v_mfma_f32_16x16x32_bf16 v[16:19], v[4:7], v[208:211], 0
	v_cmp_eq_u32_e64 s[10:11], 0, v99
	s_waitcnt lgkmcnt(6)
	v_mfma_f32_16x16x32_bf16 v[28:31], v[12:15], v[208:211], 0
	s_waitcnt lgkmcnt(5)
	v_mfma_f32_16x16x32_bf16 v[40:43], v[32:35], v[208:211], 0
	s_waitcnt lgkmcnt(4)
	v_mfma_f32_16x16x32_bf16 v[44:47], v[36:39], v[208:211], 0
	s_waitcnt lgkmcnt(3)
	v_mfma_f32_16x16x32_bf16 v[62:65], v[50:53], v[208:211], 0
	s_waitcnt vmcnt(5)
	v_mfma_f32_16x16x32_bf16 v[50:53], v[50:53], v[212:215], 0
	s_waitcnt lgkmcnt(2)
	v_mfma_f32_16x16x32_bf16 v[100:103], v[54:57], v[208:211], 0
	v_mfma_f32_16x16x32_bf16 v[104:107], v[54:57], v[212:215], 0
	v_lshl_add_u32 v55, v164, 3, s8
	v_add_u32_e32 v54, s38, v48
	s_waitcnt lgkmcnt(1)
	v_mfma_f32_16x16x32_bf16 v[120:123], v[58:61], v[208:211], 0
	v_mfma_f32_16x16x32_bf16 v[132:135], v[58:61], v[212:215], 0
	v_add_u32_e32 v59, 0x19800, v55
	v_ashrrev_i32_e32 v55, 31, v54
	v_lshlrev_b32_e32 v58, 1, v48
	s_waitcnt lgkmcnt(0)
	v_mfma_f32_16x16x32_bf16 v[0:3], v[116:119], v[208:211], 0
	v_lshl_add_u32 v61, v99, 7, v59
	v_lshl_add_u64 v[56:57], v[54:55], 3, s[4:5]
	v_mfma_f32_16x16x32_bf16 v[4:7], v[4:7], v[212:215], 0
	v_mfma_f32_16x16x32_bf16 v[12:15], v[12:15], v[212:215], 0
	v_mfma_f32_16x16x32_bf16 v[32:35], v[32:35], v[212:215], 0
	v_mfma_f32_16x16x32_bf16 v[36:39], v[36:39], v[212:215], 0
	v_mfma_f32_16x16x32_bf16 v[20:23], v[116:119], v[212:215], 0
	ds_read_b128 v[116:119], v68 offset:64
	ds_read_b128 v[136:139], v68 offset:4416
	s_waitcnt lgkmcnt(1)
	v_mfma_f32_16x16x32_bf16 v[16:19], v[116:119], v[216:219], v[16:19]
	s_waitcnt vmcnt(4)
	v_mfma_f32_16x16x32_bf16 v[4:7], v[116:119], v[220:223], v[4:7]
	s_waitcnt lgkmcnt(0)
	v_mfma_f32_16x16x32_bf16 v[28:31], v[136:139], v[216:219], v[28:31]
	v_mfma_f32_16x16x32_bf16 v[12:15], v[136:139], v[220:223], v[12:15]
	ds_read_b128 v[116:119], v68 offset:8768
	ds_read_b128 v[136:139], v68 offset:13120
	s_waitcnt lgkmcnt(1)
	v_mfma_f32_16x16x32_bf16 v[40:43], v[116:119], v[216:219], v[40:43]
	v_mfma_f32_16x16x32_bf16 v[32:35], v[116:119], v[220:223], v[32:35]
	s_waitcnt lgkmcnt(0)
	v_mfma_f32_16x16x32_bf16 v[44:47], v[136:139], v[216:219], v[44:47]
	v_mfma_f32_16x16x32_bf16 v[36:39], v[136:139], v[220:223], v[36:39]
	ds_read_b128 v[116:119], v68 offset:17472
	ds_read_b128 v[136:139], v68 offset:21824
	s_waitcnt lgkmcnt(1)
	v_mfma_f32_16x16x32_bf16 v[62:65], v[116:119], v[216:219], v[62:65]
	v_mfma_f32_16x16x32_bf16 v[50:53], v[116:119], v[220:223], v[50:53]
	s_waitcnt lgkmcnt(0)
	v_mfma_f32_16x16x32_bf16 v[100:103], v[136:139], v[216:219], v[100:103]
	v_mfma_f32_16x16x32_bf16 v[104:107], v[136:139], v[220:223], v[104:107]
	ds_read_b128 v[116:119], v68 offset:26176
	ds_read_b128 v[136:139], v68 offset:30528
	s_waitcnt lgkmcnt(1)
	v_mfma_f32_16x16x32_bf16 v[120:123], v[116:119], v[216:219], v[120:123]
	v_mfma_f32_16x16x32_bf16 v[116:119], v[116:119], v[220:223], v[132:135]
	s_waitcnt lgkmcnt(0)
	v_mfma_f32_16x16x32_bf16 v[0:3], v[136:139], v[216:219], v[0:3]
	v_mfma_f32_16x16x32_bf16 v[8:11], v[136:139], v[220:223], v[20:23]
	s_nop 2
	ds_read_b128 v[20:23], v68 offset:128
	ds_read_b128 v[24:27], v68 offset:4480
	s_waitcnt vmcnt(3) lgkmcnt(1)
	v_mfma_f32_16x16x32_bf16 v[16:19], v[20:23], v[224:227], v[16:19]
	s_waitcnt vmcnt(1)
	v_mfma_f32_16x16x32_bf16 v[4:7], v[20:23], v[228:231], v[4:7]
	s_waitcnt lgkmcnt(0)
	v_mfma_f32_16x16x32_bf16 v[20:23], v[24:27], v[224:227], v[28:31]
	v_mfma_f32_16x16x32_bf16 v[12:15], v[24:27], v[228:231], v[12:15]
	ds_read_b128 v[24:27], v68 offset:8832
	s_nop 0
	ds_read_b128 v[28:31], v68 offset:13184
	s_waitcnt lgkmcnt(1)
	v_mfma_f32_16x16x32_bf16 v[40:43], v[24:27], v[224:227], v[40:43]
	v_mfma_f32_16x16x32_bf16 v[24:27], v[24:27], v[228:231], v[32:35]
	s_waitcnt lgkmcnt(0)
	v_mfma_f32_16x16x32_bf16 v[32:35], v[28:31], v[224:227], v[44:47]
	v_mfma_f32_16x16x32_bf16 v[28:31], v[28:31], v[228:231], v[36:39]
	s_nop 2
	ds_read_b128 v[36:39], v68 offset:17536
	ds_read_b128 v[44:47], v68 offset:21888
	s_waitcnt lgkmcnt(1)
	v_mfma_f32_16x16x32_bf16 v[62:65], v[36:39], v[224:227], v[62:65]
	v_mfma_f32_16x16x32_bf16 v[50:53], v[36:39], v[228:231], v[50:53]
	s_waitcnt lgkmcnt(0)
	v_mfma_f32_16x16x32_bf16 v[100:103], v[44:47], v[224:227], v[100:103]
	v_mfma_f32_16x16x32_bf16 v[104:107], v[44:47], v[228:231], v[104:107]
	ds_read_b128 v[36:39], v68 offset:26240
	ds_read_b128 v[44:47], v68 offset:30592
	s_waitcnt lgkmcnt(1)
	v_mfma_f32_16x16x32_bf16 v[120:123], v[36:39], v[224:227], v[120:123]
	v_mfma_f32_16x16x32_bf16 v[116:119], v[36:39], v[228:231], v[116:119]
	s_waitcnt lgkmcnt(0)
	v_mfma_f32_16x16x32_bf16 v[0:3], v[44:47], v[224:227], v[0:3]
	v_mfma_f32_16x16x32_bf16 v[108:111], v[44:47], v[228:231], v[8:11]
	s_nop 2
	ds_read_b128 v[8:11], v68 offset:192
	ds_read_b128 v[36:39], v68 offset:4544
	s_waitcnt lgkmcnt(1)
	v_mfma_f32_16x16x32_bf16 v[124:127], v[8:11], v[232:235], v[16:19]
	s_waitcnt vmcnt(0)
	v_mfma_f32_16x16x32_bf16 v[132:135], v[8:11], v[236:239], v[4:7]
	s_nop 2
	ds_read_b128 v[4:7], v68 offset:8896
	ds_read_b128 v[8:11], v68 offset:13248
	s_waitcnt lgkmcnt(2)
	v_mfma_f32_16x16x32_bf16 v[136:139], v[36:39], v[232:235], v[20:23]
	v_mfma_f32_16x16x32_bf16 v[140:143], v[36:39], v[236:239], v[12:15]
	s_waitcnt lgkmcnt(1)
; DI float bf2f(unsigned short b) { return __uint_as_float(((unsigned)b) << 16); }
; DI float ex2(float x) { return __builtin_amdgcn_exp2f(x); }
; DI void lru_tile(const Params& p, unsigned char* shm, int c, int nb, const LruPar par) {
;     ...
;             for (int gt = 0; gt < 2; ++gt) bfr[s][gt] = *(const bf16x8*)(LWT + ((size_t)((d * 2 + gt) * 16 + nb) * 128 + chl) * 128 + s * 32 + q * 8);
; #pragma unroll
;         for (int s = 0; s < 4; ++s) {
; #pragma unroll
;             for (int rt = 0; rt < 8; ++rt) {
;                 const bf16x8 af = *(const bf16x8*)(UB + (rt * 16 + col) * LDU + s * 32 + q * 8);
; #pragma unroll
;                 for (int gt = 0; gt < 2; ++gt) acc[gt][rt] = __builtin_amdgcn_mfma_f32_16x16x32_bf16(af, bfr[s][gt], acc[gt][rt], 0, 0, 0);
;             }
;             __builtin_amdgcn_sched_barrier(0);
;         }
;         const f32x2 nl2 = {-LOG2E, -LOG2E}, nbr2 = {par.nbr[d], par.nbr[d]}, nbi2 = {par.nbi[d], par.nbi[d]}, cd2 = {par.cdec[d], par.cdec[d]}, one2 = {1.f, 1.f};
;         float hl[8][4], pc[8][4];
; #pragma unroll
;         for (int rt = 0; rt < 8; ++rt) {
;             float av[4], bv[4];
; #pragma unroll
;             for (int jp = 0; jp < 2; ++jp) {
;                 const f32x2 xr = {acc[0][rt][2 * jp], acc[0][rt][2 * jp + 1]}, xi = {acc[1][rt][2 * jp], acc[1][rt][2 * jp + 1]};
;                 f32x2 er = xr * nl2 + nbr2, ei = xi * nl2 + nbi2;
;                 er = (f32x2){ex2(er[0]), ex2(er[1])} + one2; ei = (f32x2){ex2(ei[0]), ex2(ei[1])} + one2;
;                 const f32x2 r = {rcpf_(er[0]), rcpf_(er[1])}, ig = {rcpf_(ei[0]), rcpf_(ei[1])};
;                 const f32x2 la = r * cd2;
;                 const f32x2 a = {ex2(la[0]), ex2(la[1])};
;                 const f32x2 om = one2 - a * a;
;                 const f32x2 sc = {__builtin_amdgcn_sqrtf(om[0]), __builtin_amdgcn_sqrtf(om[1])};
;                 const f32x2 u2 = {bf2f(UB[(rt * 16 + 4 * q + 2 * jp) * LDU + chl]), bf2f(UB[(rt * 16 + 4 * q + 2 * jp + 1) * LDU + chl])};
;                 const f32x2 b2 = sc * ig * u2;
;                 av[2 * jp] = a[0]; av[2 * jp + 1] = a[1]; bv[2 * jp] = b2[0]; bv[2 * jp + 1] = b2[1];
;             }
;             float h = 0.f, P = 1.f;
;             if (d == 0) {
; #pragma unroll
;                 for (int j = 0; j < 4; ++j) { h = fmaf(av[j], h, bv[j]); P *= av[j]; hl[rt][j] = h; pc[rt][j] = P; }
	v_mfma_f32_16x16x32_bf16 v[44:47], v[4:7], v[232:235], v[40:43]
	v_mfma_f32_16x16x32_bf16 v[40:43], v[4:7], v[236:239], v[24:27]
	s_waitcnt lgkmcnt(0)
	v_mfma_f32_16x16x32_bf16 v[36:39], v[8:11], v[232:235], v[32:35]
	v_mfma_f32_16x16x32_bf16 v[32:35], v[8:11], v[236:239], v[28:31]
	ds_read_b128 v[4:7], v68 offset:17600
	ds_read_b128 v[8:11], v68 offset:21952
	s_waitcnt lgkmcnt(1)
	v_mfma_f32_16x16x32_bf16 v[28:31], v[4:7], v[232:235], v[62:65]
	v_mfma_f32_16x16x32_bf16 v[24:27], v[4:7], v[236:239], v[50:53]
	ds_read_b128 v[4:7], v68 offset:26304
	s_nop 1
	ds_read_b128 v[50:53], v68 offset:30656
	s_waitcnt lgkmcnt(2)
	v_mfma_f32_16x16x32_bf16 v[20:23], v[8:11], v[232:235], v[100:103]
	v_mfma_f32_16x16x32_bf16 v[16:19], v[8:11], v[236:239], v[104:107]
	s_waitcnt lgkmcnt(1)
	v_mfma_f32_16x16x32_bf16 v[12:15], v[4:7], v[232:235], v[120:123]
	v_mfma_f32_16x16x32_bf16 v[8:11], v[4:7], v[236:239], v[116:119]
	s_waitcnt lgkmcnt(0)
	v_mfma_f32_16x16x32_bf16 v[4:7], v[50:53], v[232:235], v[0:3]
	v_mfma_f32_16x16x32_bf16 v[0:3], v[50:53], v[236:239], v[108:111]
	s_add_u32 s74, s34, 0x100000
	s_addc_u32 s75, s35, 0
	s_add_u32 s76, s34, 0x180000
	s_addc_u32 s77, s35, 0
	global_load_dwordx4 v[208:211], v240, s[74:75]
	global_load_dwordx4 v[216:219], v240, s[74:75] offset:64
	global_load_dwordx4 v[212:215], v240, s[76:77]
	global_load_dwordx4 v[220:223], v240, s[76:77] offset:64
	global_load_dwordx4 v[224:227], v240, s[74:75] offset:128
	global_load_dwordx4 v[228:231], v240, s[74:75] offset:192
	global_load_dwordx4 v[232:235], v240, s[76:77] offset:128
	global_load_dwordx4 v[236:239], v240, s[76:77] offset:192
	v_fma_f32 v52, -v126, s50, v82
	v_fma_f32 v53, -v127, s50, v82
	v_pk_fma_f32 v[54:55], v[134:135], s[50:51], v[86:87] op_sel_hi:[1,0,0] neg_lo:[1,0,0] neg_hi:[1,0,0]
	v_exp_f32_e32 v52, v52
	v_exp_f32_e32 v53, v53
	v_pk_fma_f32 v[50:51], v[124:125], s[50:51], v[82:83] op_sel_hi:[1,0,0] neg_lo:[1,0,0] neg_hi:[1,0,0]
	v_exp_f32_e32 v54, v54
	v_exp_f32_e32 v55, v55
	v_pk_add_f32 v[52:53], v[52:53], 1.0 op_sel_hi:[1,0]
	v_exp_f32_e32 v50, v50
	v_rcp_f32_e32 v52, v52
	v_rcp_f32_e32 v53, v53
	v_exp_f32_e32 v51, v51
	v_mul_u32_u24_e32 v95, 0x220, v99
	v_lshlrev_b32_e32 v60, 1, v95
	v_pk_mul_f32 v[52:53], v[92:93], v[52:53] op_sel_hi:[0,1]
	v_exp_f32_e32 v62, v52
	v_exp_f32_e32 v63, v53
	v_pk_add_f32 v[52:53], v[54:55], 1.0 op_sel_hi:[1,0]
	v_pk_add_f32 v[50:51], v[50:51], 1.0 op_sel_hi:[1,0]
	v_rcp_f32_e32 v52, v52
	v_pk_fma_f32 v[54:55], v[62:63], v[62:63], 1.0 op_sel_hi:[1,1,0] neg_lo:[1,0,0] neg_hi:[1,0,0]
	v_rcp_f32_e32 v53, v53
	v_sqrt_f32_e32 v54, v54
	v_sqrt_f32_e32 v55, v55
	v_rcp_f32_e32 v50, v50
	v_rcp_f32_e32 v51, v51
	v_add3_u32 v68, 0, v58, v60
	v_pk_mul_f32 v[52:53], v[52:53], v[54:55]
	v_pk_fma_f32 v[54:55], v[132:133], s[50:51], v[86:87] op_sel_hi:[1,0,0] neg_lo:[1,0,0] neg_hi:[1,0,0]
	v_pk_mul_f32 v[50:51], v[92:93], v[50:51] op_sel_hi:[0,1]
	v_exp_f32_e32 v54, v54
	v_exp_f32_e32 v55, v55
	v_exp_f32_e32 v50, v50
	v_exp_f32_e32 v51, v51
	v_add3_u32 v97, 0, v60, v58
	ds_read_u16 v58, v68 offset:544
	ds_read_u16 v60, v97 offset:816
	v_pk_add_f32 v[54:55], v[54:55], 1.0 op_sel_hi:[1,0]
	ds_read_u16 v96, v97 offset:272
	ds_read_u16 v98, v68
	v_rcp_f32_e32 v64, v54
	v_rcp_f32_e32 v65, v55
	v_pk_fma_f32 v[54:55], v[50:51], v[50:51], 1.0 op_sel_hi:[1,1,0] neg_lo:[1,0,0] neg_hi:[1,0,0]
	s_nop 0
	v_sqrt_f32_e32 v66, v54
	v_sqrt_f32_e32 v67, v55
	s_waitcnt lgkmcnt(3)
	v_lshlrev_b32_e32 v54, 16, v58
	s_waitcnt lgkmcnt(2)
	v_lshlrev_b32_e32 v55, 16, v60
	v_pk_mul_f32 v[54:55], v[52:53], v[54:55]
	v_pk_mul_f32 v[52:53], v[64:65], v[66:67]
	s_waitcnt lgkmcnt(0)
	v_lshlrev_b32_e32 v64, 16, v98
	v_lshlrev_b32_e32 v65, 16, v96
	v_pk_mul_f32 v[52:53], v[52:53], v[64:65]
	s_nop 0
	v_fma_f32 v52, 0, v50, v52
	v_fmac_f32_e32 v53, v51, v52
	v_mul_f32_e32 v51, v50, v51
	v_fma_f32 v58, v62, v53, v54
	v_mul_f32_e32 v60, v62, v51
	v_fmac_f32_e32 v55, v63, v58
	v_mul_f32_e32 v54, v63, v60
	ds_write_b64 v61, v[54:55]
	v_pk_fma_f32 v[64:65], v[138:139], s[50:51], v[82:83] op_sel_hi:[1,0,0] neg_lo:[1,0,0] neg_hi:[1,0,0]
	v_pk_fma_f32 v[66:67], v[142:143], s[50:51], v[86:87] op_sel_hi:[1,0,0] neg_lo:[1,0,0] neg_hi:[1,0,0]
	v_exp_f32_e32 v64, v64
	v_exp_f32_e32 v65, v65
	v_pk_fma_f32 v[62:63], v[136:137], s[50:51], v[82:83] op_sel_hi:[1,0,0] neg_lo:[1,0,0] neg_hi:[1,0,0]
	v_exp_f32_e32 v66, v66
	v_exp_f32_e32 v67, v67
	v_pk_add_f32 v[64:65], v[64:65], 1.0 op_sel_hi:[1,0]
	v_exp_f32_e32 v62, v62
	v_rcp_f32_e32 v64, v64
	v_rcp_f32_e32 v65, v65
	v_exp_f32_e32 v63, v63
	ds_read_u16 v96, v68 offset:4896
	ds_read_u16 v98, v97 offset:5168
	ds_read_u16 v106, v97 offset:4624
	ds_read_u16 v107, v68 offset:4352
	v_pk_mul_f32 v[64:65], v[92:93], v[64:65] op_sel_hi:[0,1]
	v_exp_f32_e32 v100, v64
	v_exp_f32_e32 v101, v65
	v_pk_add_f32 v[64:65], v[66:67], 1.0 op_sel_hi:[1,0]
	v_pk_add_f32 v[62:63], v[62:63], 1.0 op_sel_hi:[1,0]
	v_rcp_f32_e32 v64, v64
	v_pk_fma_f32 v[66:67], v[100:101], v[100:101], 1.0 op_sel_hi:[1,1,0] neg_lo:[1,0,0] neg_hi:[1,0,0]
	v_rcp_f32_e32 v65, v65
	v_sqrt_f32_e32 v66, v66
	v_sqrt_f32_e32 v67, v67
	v_rcp_f32_e32 v62, v62
	v_rcp_f32_e32 v63, v63
	v_pk_mul_f32 v[64:65], v[64:65], v[66:67]
	v_pk_fma_f32 v[66:67], v[140:141], s[50:51], v[86:87] op_sel_hi:[1,0,0] neg_lo:[1,0,0] neg_hi:[1,0,0]
	v_pk_mul_f32 v[62:63], v[92:93], v[62:63] op_sel_hi:[0,1]
	v_exp_f32_e32 v66, v66
	v_exp_f32_e32 v67, v67
	v_exp_f32_e32 v62, v62
	v_exp_f32_e32 v63, v63
	v_pk_add_f32 v[66:67], v[66:67], 1.0 op_sel_hi:[1,0]
	s_nop 0
	v_rcp_f32_e32 v102, v66
	v_rcp_f32_e32 v103, v67
	v_pk_fma_f32 v[66:67], v[62:63], v[62:63], 1.0 op_sel_hi:[1,1,0] neg_lo:[1,0,0] neg_hi:[1,0,0]
	s_nop 0
	v_sqrt_f32_e32 v104, v66
	v_sqrt_f32_e32 v105, v67
	s_waitcnt lgkmcnt(3)
; DI float bf2f(unsigned short b) { return __uint_as_float(((unsigned)b) << 16); }
; DI float ex2(float x) { return __builtin_amdgcn_exp2f(x); }
; DI float rcpf_(float x) { return __builtin_amdgcn_rcpf(x); }
; DI void lru_tile(const Params& p, unsigned char* shm, int c, int nb, const LruPar par) {
;     ...
;         const f32x2 nl2 = {-LOG2E, -LOG2E}, nbr2 = {par.nbr[d], par.nbr[d]}, nbi2 = {par.nbi[d], par.nbi[d]}, cd2 = {par.cdec[d], par.cdec[d]}, one2 = {1.f, 1.f};
;         float hl[8][4], pc[8][4];
; #pragma unroll
;         for (int rt = 0; rt < 8; ++rt) {
;             float av[4], bv[4];
; #pragma unroll
;             for (int jp = 0; jp < 2; ++jp) {
;                 const f32x2 xr = {acc[0][rt][2 * jp], acc[0][rt][2 * jp + 1]}, xi = {acc[1][rt][2 * jp], acc[1][rt][2 * jp + 1]};
;                 f32x2 er = xr * nl2 + nbr2, ei = xi * nl2 + nbi2;
;                 er = (f32x2){ex2(er[0]), ex2(er[1])} + one2; ei = (f32x2){ex2(ei[0]), ex2(ei[1])} + one2;
;                 const f32x2 r = {rcpf_(er[0]), rcpf_(er[1])}, ig = {rcpf_(ei[0]), rcpf_(ei[1])};
;                 const f32x2 la = r * cd2;
;                 const f32x2 a = {ex2(la[0]), ex2(la[1])};
;                 const f32x2 om = one2 - a * a;
;                 const f32x2 sc = {__builtin_amdgcn_sqrtf(om[0]), __builtin_amdgcn_sqrtf(om[1])};
;                 const f32x2 u2 = {bf2f(UB[(rt * 16 + 4 * q + 2 * jp) * LDU + chl]), bf2f(UB[(rt * 16 + 4 * q + 2 * jp + 1) * LDU + chl])};
;                 const f32x2 b2 = sc * ig * u2;
;                 av[2 * jp] = a[0]; av[2 * jp + 1] = a[1]; bv[2 * jp] = b2[0]; bv[2 * jp + 1] = b2[1];
;             }
;             float h = 0.f, P = 1.f;
;             if (d == 0) {
; #pragma unroll
;                 for (int j = 0; j < 4; ++j) { h = fmaf(av[j], h, bv[j]); P *= av[j]; hl[rt][j] = h; pc[rt][j] = P; }
;             } else {
; #pragma unroll
;                 for (int j = 3; j >= 0; --j) { h = fmaf(av[j], h, bv[j]); P *= av[j]; hl[rt][j] = h; pc[rt][j] = P; }
;             }
;             AG[(rt * 4 + q) * 16 + col] = (f32x2){P, h};
;             __builtin_amdgcn_sched_barrier(0);
	v_lshlrev_b32_e32 v66, 16, v96
	s_waitcnt lgkmcnt(2)
	v_lshlrev_b32_e32 v67, 16, v98
	v_pk_mul_f32 v[66:67], v[64:65], v[66:67]
	v_pk_mul_f32 v[64:65], v[102:103], v[104:105]
	s_waitcnt lgkmcnt(0)
	v_lshlrev_b32_e32 v102, 16, v107
	v_lshlrev_b32_e32 v103, 16, v106
	v_pk_mul_f32 v[64:65], v[64:65], v[102:103]
	s_nop 0
	v_fma_f32 v64, 0, v62, v64
	v_fmac_f32_e32 v65, v63, v64
	v_mul_f32_e32 v63, v62, v63
	v_fma_f32 v96, v100, v65, v66
	v_mul_f32_e32 v98, v100, v63
	v_fmac_f32_e32 v67, v101, v96
	v_mul_f32_e32 v66, v101, v98
	ds_write_b64 v61, v[66:67] offset:512
	v_pk_fma_f32 v[46:47], v[46:47], s[50:51], v[82:83] op_sel_hi:[1,0,0] neg_lo:[1,0,0] neg_hi:[1,0,0]
	v_pk_fma_f32 v[44:45], v[44:45], s[50:51], v[82:83] op_sel_hi:[1,0,0] neg_lo:[1,0,0] neg_hi:[1,0,0]
	v_exp_f32_e32 v46, v46
	v_exp_f32_e32 v47, v47
	v_exp_f32_e32 v44, v44
	v_exp_f32_e32 v45, v45
	v_pk_fma_f32 v[42:43], v[42:43], s[50:51], v[86:87] op_sel_hi:[1,0,0] neg_lo:[1,0,0] neg_hi:[1,0,0]
	v_pk_add_f32 v[46:47], v[46:47], 1.0 op_sel_hi:[1,0]
	v_exp_f32_e32 v42, v42
	v_rcp_f32_e32 v46, v46
	v_rcp_f32_e32 v47, v47
	v_pk_add_f32 v[44:45], v[44:45], 1.0 op_sel_hi:[1,0]
	v_exp_f32_e32 v43, v43
	v_rcp_f32_e32 v44, v44
	v_pk_mul_f32 v[46:47], v[92:93], v[46:47] op_sel_hi:[0,1]
	v_exp_f32_e32 v46, v46
	v_exp_f32_e32 v47, v47
	v_rcp_f32_e32 v45, v45
	v_pk_add_f32 v[42:43], v[42:43], 1.0 op_sel_hi:[1,0]
	v_pk_fma_f32 v[40:41], v[40:41], s[50:51], v[86:87] op_sel_hi:[1,0,0] neg_lo:[1,0,0] neg_hi:[1,0,0]
	v_pk_fma_f32 v[100:101], v[46:47], v[46:47], 1.0 op_sel_hi:[1,1,0] neg_lo:[1,0,0] neg_hi:[1,0,0]
	v_rcp_f32_e32 v42, v42
	v_rcp_f32_e32 v43, v43
	v_sqrt_f32_e32 v102, v100
	v_sqrt_f32_e32 v103, v101
	v_pk_mul_f32 v[44:45], v[92:93], v[44:45] op_sel_hi:[0,1]
	v_exp_f32_e32 v100, v44
	v_exp_f32_e32 v40, v40
	v_exp_f32_e32 v41, v41
	v_exp_f32_e32 v101, v45
	v_pk_mul_f32 v[42:43], v[42:43], v[102:103]
	ds_read_u16 v102, v68 offset:9248
	ds_read_u16 v103, v97 offset:9520
	v_pk_add_f32 v[40:41], v[40:41], 1.0 op_sel_hi:[1,0]
	v_pk_fma_f32 v[44:45], v[100:101], v[100:101], 1.0 op_sel_hi:[1,1,0] neg_lo:[1,0,0] neg_hi:[1,0,0]
	ds_read_u16 v106, v97 offset:8976
	ds_read_u16 v107, v68 offset:8704
	v_rcp_f32_e32 v40, v40
	v_rcp_f32_e32 v41, v41
	v_sqrt_f32_e32 v44, v44
	v_sqrt_f32_e32 v45, v45
	s_waitcnt lgkmcnt(3)
	v_lshlrev_b32_e32 v102, 16, v102
	s_waitcnt lgkmcnt(2)
	v_lshlrev_b32_e32 v103, 16, v103
	v_pk_mul_f32 v[104:105], v[42:43], v[102:103]
	v_pk_mul_f32 v[40:41], v[40:41], v[44:45]
	s_waitcnt lgkmcnt(0)
	v_lshlrev_b32_e32 v42, 16, v107
	v_lshlrev_b32_e32 v43, 16, v106
	v_pk_mul_f32 v[102:103], v[40:41], v[42:43]
	s_nop 0
	v_fma_f32 v102, 0, v100, v102
	v_fmac_f32_e32 v103, v101, v102
	v_mul_f32_e32 v101, v100, v101
	v_fma_f32 v106, v46, v103, v104
	v_mul_f32_e32 v108, v46, v101
	v_fmac_f32_e32 v105, v47, v106
	v_mul_f32_e32 v104, v47, v108
	ds_write_b64 v61, v[104:105] offset:1024
	v_pk_fma_f32 v[38:39], v[38:39], s[50:51], v[82:83] op_sel_hi:[1,0,0] neg_lo:[1,0,0] neg_hi:[1,0,0]
	v_pk_fma_f32 v[36:37], v[36:37], s[50:51], v[82:83] op_sel_hi:[1,0,0] neg_lo:[1,0,0] neg_hi:[1,0,0]
	v_exp_f32_e32 v38, v38
	v_exp_f32_e32 v39, v39
	v_exp_f32_e32 v36, v36
	v_exp_f32_e32 v37, v37
	v_pk_fma_f32 v[34:35], v[34:35], s[50:51], v[86:87] op_sel_hi:[1,0,0] neg_lo:[1,0,0] neg_hi:[1,0,0]
	v_pk_add_f32 v[38:39], v[38:39], 1.0 op_sel_hi:[1,0]
	v_exp_f32_e32 v34, v34
	v_rcp_f32_e32 v38, v38
	v_rcp_f32_e32 v39, v39
	v_pk_add_f32 v[36:37], v[36:37], 1.0 op_sel_hi:[1,0]
	v_exp_f32_e32 v35, v35
	v_rcp_f32_e32 v36, v36
	v_pk_mul_f32 v[38:39], v[92:93], v[38:39] op_sel_hi:[0,1]
	v_exp_f32_e32 v38, v38
	v_exp_f32_e32 v39, v39
	v_rcp_f32_e32 v37, v37
	v_pk_add_f32 v[34:35], v[34:35], 1.0 op_sel_hi:[1,0]
	v_pk_fma_f32 v[32:33], v[32:33], s[50:51], v[86:87] op_sel_hi:[1,0,0] neg_lo:[1,0,0] neg_hi:[1,0,0]
	v_pk_fma_f32 v[40:41], v[38:39], v[38:39], 1.0 op_sel_hi:[1,1,0] neg_lo:[1,0,0] neg_hi:[1,0,0]
	v_rcp_f32_e32 v34, v34
	v_rcp_f32_e32 v35, v35
	v_sqrt_f32_e32 v40, v40
	v_sqrt_f32_e32 v41, v41
	v_pk_mul_f32 v[36:37], v[92:93], v[36:37] op_sel_hi:[0,1]
	v_exp_f32_e32 v110, v36
	v_exp_f32_e32 v32, v32
	v_exp_f32_e32 v33, v33
	v_exp_f32_e32 v111, v37
	v_pk_mul_f32 v[34:35], v[34:35], v[40:41]
	ds_read_u16 v40, v68 offset:13600
	ds_read_u16 v41, v97 offset:13872
	v_pk_add_f32 v[32:33], v[32:33], 1.0 op_sel_hi:[1,0]
	v_pk_fma_f32 v[36:37], v[110:111], v[110:111], 1.0 op_sel_hi:[1,1,0] neg_lo:[1,0,0] neg_hi:[1,0,0]
	ds_read_u16 v42, v97 offset:13328
	ds_read_u16 v43, v68 offset:13056
	v_rcp_f32_e32 v32, v32
	v_rcp_f32_e32 v33, v33
	v_sqrt_f32_e32 v36, v36
	v_sqrt_f32_e32 v37, v37
	s_waitcnt lgkmcnt(3)
	v_lshlrev_b32_e32 v40, 16, v40
	s_waitcnt lgkmcnt(2)
	v_lshlrev_b32_e32 v41, 16, v41
	v_pk_mul_f32 v[114:115], v[34:35], v[40:41]
	v_pk_mul_f32 v[32:33], v[32:33], v[36:37]
	s_waitcnt lgkmcnt(0)
; DI float bf2f(unsigned short b) { return __uint_as_float(((unsigned)b) << 16); }
; DI float ex2(float x) { return __builtin_amdgcn_exp2f(x); }
; DI float rcpf_(float x) { return __builtin_amdgcn_rcpf(x); }
; DI void lru_tile(const Params& p, unsigned char* shm, int c, int nb, const LruPar par) {
;     ...
;         const f32x2 nl2 = {-LOG2E, -LOG2E}, nbr2 = {par.nbr[d], par.nbr[d]}, nbi2 = {par.nbi[d], par.nbi[d]}, cd2 = {par.cdec[d], par.cdec[d]}, one2 = {1.f, 1.f};
;         float hl[8][4], pc[8][4];
; #pragma unroll
;         for (int rt = 0; rt < 8; ++rt) {
;             float av[4], bv[4];
; #pragma unroll
;             for (int jp = 0; jp < 2; ++jp) {
;                 const f32x2 xr = {acc[0][rt][2 * jp], acc[0][rt][2 * jp + 1]}, xi = {acc[1][rt][2 * jp], acc[1][rt][2 * jp + 1]};
;                 f32x2 er = xr * nl2 + nbr2, ei = xi * nl2 + nbi2;
;                 er = (f32x2){ex2(er[0]), ex2(er[1])} + one2; ei = (f32x2){ex2(ei[0]), ex2(ei[1])} + one2;
;                 const f32x2 r = {rcpf_(er[0]), rcpf_(er[1])}, ig = {rcpf_(ei[0]), rcpf_(ei[1])};
;                 const f32x2 la = r * cd2;
;                 const f32x2 a = {ex2(la[0]), ex2(la[1])};
;                 const f32x2 om = one2 - a * a;
;                 const f32x2 sc = {__builtin_amdgcn_sqrtf(om[0]), __builtin_amdgcn_sqrtf(om[1])};
;                 const f32x2 u2 = {bf2f(UB[(rt * 16 + 4 * q + 2 * jp) * LDU + chl]), bf2f(UB[(rt * 16 + 4 * q + 2 * jp + 1) * LDU + chl])};
;                 const f32x2 b2 = sc * ig * u2;
;                 av[2 * jp] = a[0]; av[2 * jp + 1] = a[1]; bv[2 * jp] = b2[0]; bv[2 * jp + 1] = b2[1];
;             }
;             float h = 0.f, P = 1.f;
;             if (d == 0) {
; #pragma unroll
;                 for (int j = 0; j < 4; ++j) { h = fmaf(av[j], h, bv[j]); P *= av[j]; hl[rt][j] = h; pc[rt][j] = P; }
;             } else {
; #pragma unroll
;                 for (int j = 3; j >= 0; --j) { h = fmaf(av[j], h, bv[j]); P *= av[j]; hl[rt][j] = h; pc[rt][j] = P; }
;             }
;             AG[(rt * 4 + q) * 16 + col] = (f32x2){P, h};
;             __builtin_amdgcn_sched_barrier(0);
	v_lshlrev_b32_e32 v34, 16, v43
	v_lshlrev_b32_e32 v35, 16, v42
	v_pk_mul_f32 v[112:113], v[32:33], v[34:35]
	s_nop 0
	v_fma_f32 v112, 0, v110, v112
	v_fmac_f32_e32 v113, v111, v112
	v_mul_f32_e32 v111, v110, v111
	v_fma_f32 v116, v38, v113, v114
	v_mul_f32_e32 v118, v38, v111
	v_fmac_f32_e32 v115, v39, v116
	v_mul_f32_e32 v114, v39, v118
	ds_write_b64 v61, v[114:115] offset:1536
	v_pk_fma_f32 v[30:31], v[30:31], s[50:51], v[82:83] op_sel_hi:[1,0,0] neg_lo:[1,0,0] neg_hi:[1,0,0]
	v_pk_fma_f32 v[28:29], v[28:29], s[50:51], v[82:83] op_sel_hi:[1,0,0] neg_lo:[1,0,0] neg_hi:[1,0,0]
	v_exp_f32_e32 v30, v30
	v_exp_f32_e32 v31, v31
	v_exp_f32_e32 v28, v28
	v_exp_f32_e32 v29, v29
	v_pk_fma_f32 v[26:27], v[26:27], s[50:51], v[86:87] op_sel_hi:[1,0,0] neg_lo:[1,0,0] neg_hi:[1,0,0]
	v_pk_add_f32 v[30:31], v[30:31], 1.0 op_sel_hi:[1,0]
	v_exp_f32_e32 v26, v26
	v_rcp_f32_e32 v30, v30
	v_rcp_f32_e32 v31, v31
	v_pk_add_f32 v[28:29], v[28:29], 1.0 op_sel_hi:[1,0]
	v_exp_f32_e32 v27, v27
	v_rcp_f32_e32 v28, v28
	v_pk_mul_f32 v[30:31], v[92:93], v[30:31] op_sel_hi:[0,1]
	v_exp_f32_e32 v30, v30
	v_exp_f32_e32 v31, v31
	v_rcp_f32_e32 v29, v29
	v_pk_add_f32 v[26:27], v[26:27], 1.0 op_sel_hi:[1,0]
	v_pk_fma_f32 v[24:25], v[24:25], s[50:51], v[86:87] op_sel_hi:[1,0,0] neg_lo:[1,0,0] neg_hi:[1,0,0]
	v_pk_fma_f32 v[32:33], v[30:31], v[30:31], 1.0 op_sel_hi:[1,1,0] neg_lo:[1,0,0] neg_hi:[1,0,0]
	v_rcp_f32_e32 v26, v26
	v_rcp_f32_e32 v27, v27
	v_sqrt_f32_e32 v32, v32
	v_sqrt_f32_e32 v33, v33
	v_pk_mul_f32 v[28:29], v[92:93], v[28:29] op_sel_hi:[0,1]
	v_exp_f32_e32 v120, v28
	v_exp_f32_e32 v24, v24
	v_exp_f32_e32 v25, v25
	v_exp_f32_e32 v121, v29
	v_pk_mul_f32 v[26:27], v[26:27], v[32:33]
	ds_read_u16 v32, v68 offset:17952
	ds_read_u16 v33, v97 offset:18224
	v_pk_add_f32 v[24:25], v[24:25], 1.0 op_sel_hi:[1,0]
	v_pk_fma_f32 v[28:29], v[120:121], v[120:121], 1.0 op_sel_hi:[1,1,0] neg_lo:[1,0,0] neg_hi:[1,0,0]
	ds_read_u16 v34, v97 offset:17680
	ds_read_u16 v35, v68 offset:17408
	v_rcp_f32_e32 v24, v24
	v_rcp_f32_e32 v25, v25
	v_sqrt_f32_e32 v28, v28
	v_sqrt_f32_e32 v29, v29
	s_waitcnt lgkmcnt(3)
	v_lshlrev_b32_e32 v32, 16, v32
	s_waitcnt lgkmcnt(2)
	v_lshlrev_b32_e32 v33, 16, v33
	v_pk_mul_f32 v[124:125], v[26:27], v[32:33]
	v_pk_mul_f32 v[24:25], v[24:25], v[28:29]
	s_waitcnt lgkmcnt(0)
	v_lshlrev_b32_e32 v26, 16, v35
	v_lshlrev_b32_e32 v27, 16, v34
	v_pk_mul_f32 v[122:123], v[24:25], v[26:27]
	s_nop 0
	v_fma_f32 v122, 0, v120, v122
	v_fmac_f32_e32 v123, v121, v122
	v_mul_f32_e32 v121, v120, v121
	v_fma_f32 v126, v30, v123, v124
	v_mul_f32_e32 v128, v30, v121
	v_fmac_f32_e32 v125, v31, v126
	v_mul_f32_e32 v124, v31, v128
	ds_write_b64 v61, v[124:125] offset:2048
	v_pk_fma_f32 v[22:23], v[22:23], s[50:51], v[82:83] op_sel_hi:[1,0,0] neg_lo:[1,0,0] neg_hi:[1,0,0]
	v_pk_fma_f32 v[20:21], v[20:21], s[50:51], v[82:83] op_sel_hi:[1,0,0] neg_lo:[1,0,0] neg_hi:[1,0,0]
	v_exp_f32_e32 v22, v22
	v_exp_f32_e32 v23, v23
	v_exp_f32_e32 v20, v20
	v_exp_f32_e32 v21, v21
	v_pk_fma_f32 v[18:19], v[18:19], s[50:51], v[86:87] op_sel_hi:[1,0,0] neg_lo:[1,0,0] neg_hi:[1,0,0]
	v_pk_add_f32 v[22:23], v[22:23], 1.0 op_sel_hi:[1,0]
	v_exp_f32_e32 v18, v18
	v_rcp_f32_e32 v22, v22
	v_rcp_f32_e32 v23, v23
	v_pk_add_f32 v[20:21], v[20:21], 1.0 op_sel_hi:[1,0]
	v_exp_f32_e32 v19, v19
	v_rcp_f32_e32 v20, v20
	v_pk_mul_f32 v[22:23], v[92:93], v[22:23] op_sel_hi:[0,1]
	v_exp_f32_e32 v22, v22
	v_exp_f32_e32 v23, v23
	v_rcp_f32_e32 v21, v21
	v_pk_add_f32 v[18:19], v[18:19], 1.0 op_sel_hi:[1,0]
	v_pk_fma_f32 v[16:17], v[16:17], s[50:51], v[86:87] op_sel_hi:[1,0,0] neg_lo:[1,0,0] neg_hi:[1,0,0]
	v_pk_fma_f32 v[24:25], v[22:23], v[22:23], 1.0 op_sel_hi:[1,1,0] neg_lo:[1,0,0] neg_hi:[1,0,0]
	v_rcp_f32_e32 v18, v18
	v_rcp_f32_e32 v19, v19
	v_sqrt_f32_e32 v24, v24
	v_sqrt_f32_e32 v25, v25
	v_pk_mul_f32 v[20:21], v[92:93], v[20:21] op_sel_hi:[0,1]
	v_exp_f32_e32 v130, v20
	v_exp_f32_e32 v16, v16
	v_exp_f32_e32 v17, v17
	v_exp_f32_e32 v131, v21
	v_pk_mul_f32 v[18:19], v[18:19], v[24:25]
	ds_read_u16 v24, v68 offset:22304
	ds_read_u16 v25, v97 offset:22576
	v_pk_add_f32 v[16:17], v[16:17], 1.0 op_sel_hi:[1,0]
	v_pk_fma_f32 v[20:21], v[130:131], v[130:131], 1.0 op_sel_hi:[1,1,0] neg_lo:[1,0,0] neg_hi:[1,0,0]
	ds_read_u16 v26, v97 offset:22032
	ds_read_u16 v27, v68 offset:21760
	v_rcp_f32_e32 v16, v16
	v_rcp_f32_e32 v17, v17
	v_sqrt_f32_e32 v20, v20
	v_sqrt_f32_e32 v21, v21
	s_waitcnt lgkmcnt(3)
	v_lshlrev_b32_e32 v24, 16, v24
	s_waitcnt lgkmcnt(2)
	v_lshlrev_b32_e32 v25, 16, v25
	v_pk_mul_f32 v[134:135], v[18:19], v[24:25]
	v_pk_mul_f32 v[16:17], v[16:17], v[20:21]
	s_waitcnt lgkmcnt(0)
; DI float bf2f(unsigned short b) { return __uint_as_float(((unsigned)b) << 16); }
; DI void lru_tile(const Params& p, unsigned char* shm, int c, int nb, const LruPar par) {
;     ...
;         const f32x2 nl2 = {-LOG2E, -LOG2E}, nbr2 = {par.nbr[d], par.nbr[d]}, nbi2 = {par.nbi[d], par.nbi[d]}, cd2 = {par.cdec[d], par.cdec[d]}, one2 = {1.f, 1.f};
;         float hl[8][4], pc[8][4];
; #pragma unroll
;         for (int rt = 0; rt < 8; ++rt) {
;             float av[4], bv[4];
; #pragma unroll
;             for (int jp = 0; jp < 2; ++jp) {
;                 const f32x2 xr = {acc[0][rt][2 * jp], acc[0][rt][2 * jp + 1]}, xi = {acc[1][rt][2 * jp], acc[1][rt][2 * jp + 1]};
;                 f32x2 er = xr * nl2 + nbr2, ei = xi * nl2 + nbi2;
;                 er = (f32x2){ex2(er[0]), ex2(er[1])} + one2; ei = (f32x2){ex2(ei[0]), ex2(ei[1])} + one2;
;                 const f32x2 r = {rcpf_(er[0]), rcpf_(er[1])}, ig = {rcpf_(ei[0]), rcpf_(ei[1])};
;                 const f32x2 la = r * cd2;
;                 const f32x2 a = {ex2(la[0]), ex2(la[1])};
;                 const f32x2 om = one2 - a * a;
;                 const f32x2 sc = {__builtin_amdgcn_sqrtf(om[0]), __builtin_amdgcn_sqrtf(om[1])};
;                 const f32x2 u2 = {bf2f(UB[(rt * 16 + 4 * q + 2 * jp) * LDU + chl]), bf2f(UB[(rt * 16 + 4 * q + 2 * jp + 1) * LDU + chl])};
;                 const f32x2 b2 = sc * ig * u2;
;                 av[2 * jp] = a[0]; av[2 * jp + 1] = a[1]; bv[2 * jp] = b2[0]; bv[2 * jp + 1] = b2[1];
;             }
;             float h = 0.f, P = 1.f;
;             if (d == 0) {
; #pragma unroll
;                 for (int j = 0; j < 4; ++j) { h = fmaf(av[j], h, bv[j]); P *= av[j]; hl[rt][j] = h; pc[rt][j] = P; }
;             } else {
; #pragma unroll
;                 for (int j = 3; j >= 0; --j) { h = fmaf(av[j], h, bv[j]); P *= av[j]; hl[rt][j] = h; pc[rt][j] = P; }
;             }
;             AG[(rt * 4 + q) * 16 + col] = (f32x2){P, h};
;             __builtin_amdgcn_sched_barrier(0);
;         }
;         asm volatile("s_waitcnt lgkmcnt(0)" ::: "memory");
;         float carry[8], pref[8]; float cin = 0.f, pa = 1.f;
; #pragma unroll
;         for (int gi = 0; gi < 32; ++gi) {
;             const int G = d == 0 ? gi : 31 - gi; const int rt = G >> 2, qq = G & 3;
;             const f32x2 ah = AG[G * 16 + col];
;             if (qq == q) { carry[rt] = cin; pref[rt] = pa; }
	v_lshlrev_b32_e32 v18, 16, v27
	v_lshlrev_b32_e32 v19, 16, v26
	v_pk_mul_f32 v[132:133], v[16:17], v[18:19]
	s_nop 0
	v_fma_f32 v132, 0, v130, v132
	v_fmac_f32_e32 v133, v131, v132
	v_mul_f32_e32 v131, v130, v131
	v_fma_f32 v136, v22, v133, v134
	v_mul_f32_e32 v138, v22, v131
	v_fmac_f32_e32 v135, v23, v136
	v_mul_f32_e32 v134, v23, v138
	ds_write_b64 v61, v[134:135] offset:2560
	v_pk_fma_f32 v[14:15], v[14:15], s[50:51], v[82:83] op_sel_hi:[1,0,0] neg_lo:[1,0,0] neg_hi:[1,0,0]
	v_pk_fma_f32 v[12:13], v[12:13], s[50:51], v[82:83] op_sel_hi:[1,0,0] neg_lo:[1,0,0] neg_hi:[1,0,0]
	v_exp_f32_e32 v14, v14
	v_exp_f32_e32 v15, v15
	v_exp_f32_e32 v12, v12
	v_exp_f32_e32 v13, v13
	v_pk_fma_f32 v[10:11], v[10:11], s[50:51], v[86:87] op_sel_hi:[1,0,0] neg_lo:[1,0,0] neg_hi:[1,0,0]
	v_pk_add_f32 v[14:15], v[14:15], 1.0 op_sel_hi:[1,0]
	v_exp_f32_e32 v10, v10
	v_rcp_f32_e32 v14, v14
	v_rcp_f32_e32 v15, v15
	v_pk_add_f32 v[12:13], v[12:13], 1.0 op_sel_hi:[1,0]
	v_exp_f32_e32 v11, v11
	v_rcp_f32_e32 v12, v12
	v_pk_mul_f32 v[14:15], v[92:93], v[14:15] op_sel_hi:[0,1]
	v_exp_f32_e32 v14, v14
	v_exp_f32_e32 v15, v15
	v_rcp_f32_e32 v13, v13
	v_pk_add_f32 v[10:11], v[10:11], 1.0 op_sel_hi:[1,0]
	v_pk_fma_f32 v[8:9], v[8:9], s[50:51], v[86:87] op_sel_hi:[1,0,0] neg_lo:[1,0,0] neg_hi:[1,0,0]
	v_pk_fma_f32 v[16:17], v[14:15], v[14:15], 1.0 op_sel_hi:[1,1,0] neg_lo:[1,0,0] neg_hi:[1,0,0]
	v_rcp_f32_e32 v10, v10
	v_rcp_f32_e32 v11, v11
	v_sqrt_f32_e32 v16, v16
	v_sqrt_f32_e32 v17, v17
	v_pk_mul_f32 v[12:13], v[92:93], v[12:13] op_sel_hi:[0,1]
	v_exp_f32_e32 v140, v12
	v_exp_f32_e32 v8, v8
	v_exp_f32_e32 v9, v9
	v_exp_f32_e32 v141, v13
	v_pk_mul_f32 v[10:11], v[10:11], v[16:17]
	ds_read_u16 v16, v68 offset:26656
	ds_read_u16 v17, v97 offset:26928
	v_pk_add_f32 v[8:9], v[8:9], 1.0 op_sel_hi:[1,0]
	v_pk_fma_f32 v[12:13], v[140:141], v[140:141], 1.0 op_sel_hi:[1,1,0] neg_lo:[1,0,0] neg_hi:[1,0,0]
	ds_read_u16 v18, v97 offset:26384
	ds_read_u16 v19, v68 offset:26112
	v_rcp_f32_e32 v8, v8
	v_rcp_f32_e32 v9, v9
	v_sqrt_f32_e32 v12, v12
	v_sqrt_f32_e32 v13, v13
	s_waitcnt lgkmcnt(3)
	v_lshlrev_b32_e32 v16, 16, v16
	s_waitcnt lgkmcnt(2)
	v_lshlrev_b32_e32 v17, 16, v17
	v_pk_mul_f32 v[144:145], v[10:11], v[16:17]
	v_pk_mul_f32 v[8:9], v[8:9], v[12:13]
	s_waitcnt lgkmcnt(0)
	v_lshlrev_b32_e32 v10, 16, v19
	v_lshlrev_b32_e32 v11, 16, v18
	v_pk_mul_f32 v[142:143], v[8:9], v[10:11]
	s_nop 0
	v_fma_f32 v142, 0, v140, v142
	v_fmac_f32_e32 v143, v141, v142
	v_mul_f32_e32 v141, v140, v141
	v_fma_f32 v146, v14, v143, v144
	v_mul_f32_e32 v148, v14, v141
	v_fmac_f32_e32 v145, v15, v146
	v_mul_f32_e32 v144, v15, v148
	ds_write_b64 v61, v[144:145] offset:3072
	v_pk_fma_f32 v[6:7], v[6:7], s[50:51], v[82:83] op_sel_hi:[1,0,0] neg_lo:[1,0,0] neg_hi:[1,0,0]
	v_pk_fma_f32 v[4:5], v[4:5], s[50:51], v[82:83] op_sel_hi:[1,0,0] neg_lo:[1,0,0] neg_hi:[1,0,0]
	v_exp_f32_e32 v6, v6
	v_exp_f32_e32 v7, v7
	v_exp_f32_e32 v4, v4
	v_exp_f32_e32 v5, v5
	v_pk_fma_f32 v[2:3], v[2:3], s[50:51], v[86:87] op_sel_hi:[1,0,0] neg_lo:[1,0,0] neg_hi:[1,0,0]
	v_pk_add_f32 v[6:7], v[6:7], 1.0 op_sel_hi:[1,0]
	v_exp_f32_e32 v2, v2
	v_rcp_f32_e32 v6, v6
	v_rcp_f32_e32 v7, v7
	v_pk_add_f32 v[4:5], v[4:5], 1.0 op_sel_hi:[1,0]
	v_exp_f32_e32 v3, v3
	v_rcp_f32_e32 v4, v4
	v_pk_mul_f32 v[6:7], v[92:93], v[6:7] op_sel_hi:[0,1]
	v_exp_f32_e32 v6, v6
	v_exp_f32_e32 v7, v7
	v_rcp_f32_e32 v5, v5
	v_pk_add_f32 v[2:3], v[2:3], 1.0 op_sel_hi:[1,0]
	v_pk_fma_f32 v[0:1], v[0:1], s[50:51], v[86:87] op_sel_hi:[1,0,0] neg_lo:[1,0,0] neg_hi:[1,0,0]
	v_pk_fma_f32 v[8:9], v[6:7], v[6:7], 1.0 op_sel_hi:[1,1,0] neg_lo:[1,0,0] neg_hi:[1,0,0]
	v_rcp_f32_e32 v2, v2
	v_rcp_f32_e32 v3, v3
	v_sqrt_f32_e32 v8, v8
	v_sqrt_f32_e32 v9, v9
	v_pk_mul_f32 v[4:5], v[92:93], v[4:5] op_sel_hi:[0,1]
	v_exp_f32_e32 v150, v4
	v_exp_f32_e32 v0, v0
	v_exp_f32_e32 v1, v1
	v_exp_f32_e32 v151, v5
	v_pk_mul_f32 v[2:3], v[2:3], v[8:9]
	ds_read_u16 v8, v68 offset:31008
	ds_read_u16 v9, v97 offset:31280
	v_pk_add_f32 v[0:1], v[0:1], 1.0 op_sel_hi:[1,0]
	v_pk_fma_f32 v[4:5], v[150:151], v[150:151], 1.0 op_sel_hi:[1,1,0] neg_lo:[1,0,0] neg_hi:[1,0,0]
	ds_read_u16 v10, v97 offset:30736
	ds_read_u16 v11, v68 offset:30464
	v_rcp_f32_e32 v0, v0
	v_rcp_f32_e32 v1, v1
	v_sqrt_f32_e32 v4, v4
	v_sqrt_f32_e32 v5, v5
	s_waitcnt lgkmcnt(3)
	v_lshlrev_b32_e32 v8, 16, v8
	s_waitcnt lgkmcnt(2)
	v_lshlrev_b32_e32 v9, 16, v9
	v_pk_mul_f32 v[154:155], v[2:3], v[8:9]
	v_pk_mul_f32 v[0:1], v[0:1], v[4:5]
	s_waitcnt lgkmcnt(0)
	v_lshlrev_b32_e32 v2, 16, v11
	v_lshlrev_b32_e32 v3, 16, v10
	v_pk_mul_f32 v[152:153], v[0:1], v[2:3]
	s_nop 0
	v_fma_f32 v152, 0, v150, v152
	v_fmac_f32_e32 v153, v151, v152
	v_mul_f32_e32 v151, v150, v151
	v_fma_f32 v156, v6, v153, v154
	v_mul_f32_e32 v158, v6, v151
	v_fmac_f32_e32 v155, v7, v156
	v_mul_f32_e32 v154, v7, v158
	ds_write_b64 v61, v[154:155] offset:3584
	s_waitcnt lgkmcnt(0)
	ds_read2_b64 v[0:3], v59 offset1:16
	v_cndmask_b32_e64 v4, v180, 1.0, s[10:11]
	v_cmp_eq_u32_e64 s[4:5], 1, v99
	v_cmp_eq_u32_e64 s[6:7], 2, v99
	v_cmp_eq_u32_e64 s[8:9], 3, v99
	s_waitcnt lgkmcnt(0)
	v_cndmask_b32_e64 v8, v4, v0, s[4:5]
	ds_read2_b64 v[4:7], v59 offset0:32 offset1:48
	v_fma_f32 v119, 0, v0, v1
	v_cndmask_b32_e64 v9, 1.0, v0, s[4:5]
	v_fma_f32 v127, v2, v119, v3
	v_pk_mul_f32 v[0:1], v[0:1], v[2:3]
	s_waitcnt lgkmcnt(0)
	v_fma_f32 v129, v4, v127, v5
	v_cndmask_b32_e64 v2, v8, v0, s[6:7]
	v_pk_mul_f32 v[4:5], v[0:1], v[4:5]
	v_cndmask_b32_e64 v8, v9, v0, s[6:7]
	v_cndmask_b32_e64 v178, v2, v4, s[8:9]
	ds_read2_b64 v[0:3], v59 offset0:64 offset1:80
	v_cndmask_b32_e64 v181, v8, v4, s[8:9]
	v_fma_f32 v137, v6, v129, v7
	v_pk_mul_f32 v[4:5], v[4:5], v[6:7]
	s_waitcnt lgkmcnt(0)
; DI void lru_tile(const Params& p, unsigned char* shm, int c, int nb, const LruPar par) {
;     ...
;         for (int s = 0; s < 4; ++s)
; #pragma unroll
;             for (int gt = 0; gt < 2; ++gt) bfr[s][gt] = *(const bf16x8*)(LWT + ((size_t)((d * 2 + gt) * 16 + nb) * 128 + chl) * 128 + s * 32 + q * 8);
; #pragma unroll
;         for (int s = 0; s < 4; ++s) {
; #pragma unroll
;             for (int rt = 0; rt < 8; ++rt) {
;                 const bf16x8 af = *(const bf16x8*)(UB + (rt * 16 + col) * LDU + s * 32 + q * 8);
; #pragma unroll
;                 for (int gt = 0; gt < 2; ++gt) acc[gt][rt] = __builtin_amdgcn_mfma_f32_16x16x32_bf16(af, bfr[s][gt], acc[gt][rt], 0, 0, 0);
;     ...
;         asm volatile("s_waitcnt lgkmcnt(0)" ::: "memory");
;         float carry[8], pref[8]; float cin = 0.f, pa = 1.f;
; #pragma unroll
;         for (int gi = 0; gi < 32; ++gi) {
;             const int G = d == 0 ? gi : 31 - gi; const int rt = G >> 2, qq = G & 3;
;             const f32x2 ah = AG[G * 16 + col];
;             if (qq == q) { carry[rt] = cin; pref[rt] = pa; }
;             cin = fmaf(ah[0], cin, ah[1]); pa *= ah[0];
;         }
;         if (q == 0) AGG[((size_t)d * 128 + c) * 2048 + chg] = (f32x2){pa, cin};
	v_fma_f32 v139, v0, v137, v1
	v_cndmask_b32_e64 v8, v162, v4, s[10:11]
	v_pk_mul_f32 v[0:1], v[4:5], v[0:1]
	ds_read2_b64 v[4:7], v59 offset0:96 offset1:112
	v_cndmask_b32_e64 v8, v8, v0, s[4:5]
	v_fma_f32 v147, v2, v139, v3
	v_pk_mul_f32 v[0:1], v[0:1], v[2:3]
	ds_read_b64 v[162:163], v59 offset:3840
	v_cndmask_b32_e64 v8, v8, v0, s[6:7]
	s_waitcnt lgkmcnt(1)
	v_fma_f32 v149, v4, v147, v5
	v_pk_mul_f32 v[4:5], v[0:1], v[4:5]
	ds_read2_b64 v[0:3], v59 offset0:128 offset1:144
	v_cndmask_b32_e64 v99, v8, v4, s[8:9]
	v_fma_f32 v157, v6, v149, v7
	v_pk_mul_f32 v[4:5], v[4:5], v[6:7]
	s_waitcnt lgkmcnt(0)
	v_fma_f32 v159, v0, v157, v1
	v_cndmask_b32_e64 v8, v91, v4, s[10:11]
	v_pk_mul_f32 v[0:1], v[4:5], v[0:1]
	ds_read2_b64 v[4:7], v59 offset0:160 offset1:176
	v_cndmask_b32_e64 v8, v8, v0, s[4:5]
	v_fma_f32 v183, v2, v159, v3
	v_pk_mul_f32 v[0:1], v[0:1], v[2:3]
	s_waitcnt lgkmcnt(0)
	v_fma_f32 v184, v4, v183, v5
	v_cndmask_b32_e64 v8, v8, v0, s[6:7]
	v_pk_mul_f32 v[4:5], v[0:1], v[4:5]
	ds_read2_b64 v[0:3], v59 offset0:192 offset1:208
	v_cndmask_b32_e64 v107, v8, v4, s[8:9]
	v_fma_f32 v185, v6, v184, v7
	v_pk_mul_f32 v[4:5], v[4:5], v[6:7]
	s_waitcnt lgkmcnt(0)
	v_fma_f32 v186, v0, v185, v1
	v_cndmask_b32_e64 v8, v89, v4, s[10:11]
	v_pk_mul_f32 v[0:1], v[4:5], v[0:1]
	ds_read2_b64 v[4:7], v59 offset0:224 offset1:240
	v_cndmask_b32_e64 v8, v8, v0, s[4:5]
	v_fma_f32 v187, v2, v186, v3
	v_pk_mul_f32 v[0:1], v[0:1], v[2:3]
	v_add_u32_e32 v89, 0x800, v59
	v_cndmask_b32_e64 v8, v8, v0, s[6:7]
	s_waitcnt lgkmcnt(0)
	v_fma_f32 v188, v4, v187, v5
	v_pk_mul_f32 v[4:5], v[0:1], v[4:5]
	ds_read2_b64 v[0:3], v89 offset1:16
	v_cndmask_b32_e64 v109, v8, v4, s[8:9]
	v_fma_f32 v189, v6, v188, v7
	v_pk_mul_f32 v[4:5], v[4:5], v[6:7]
	s_waitcnt lgkmcnt(0)
	v_fma_f32 v190, v0, v189, v1
	v_cndmask_b32_e64 v8, v85, v4, s[10:11]
	v_pk_mul_f32 v[0:1], v[4:5], v[0:1]
	ds_read2_b64 v[4:7], v89 offset0:32 offset1:48
	v_cndmask_b32_e64 v8, v8, v0, s[4:5]
	v_fma_f32 v192, v2, v190, v3
	v_pk_mul_f32 v[0:1], v[0:1], v[2:3]
	s_waitcnt lgkmcnt(0)
	v_fma_f32 v193, v4, v192, v5
	v_cndmask_b32_e64 v8, v8, v0, s[6:7]
	v_pk_mul_f32 v[4:5], v[0:1], v[4:5]
	ds_read2_b64 v[0:3], v89 offset0:64 offset1:80
	v_cndmask_b32_e64 v117, v8, v4, s[8:9]
	v_fma_f32 v194, v6, v193, v7
	v_pk_mul_f32 v[4:5], v[4:5], v[6:7]
	s_waitcnt lgkmcnt(0)
	v_fma_f32 v195, v0, v194, v1
	v_cndmask_b32_e64 v8, v81, v4, s[10:11]
	v_pk_mul_f32 v[0:1], v[4:5], v[0:1]
	ds_read2_b64 v[4:7], v89 offset0:96 offset1:112
	v_cndmask_b32_e64 v8, v8, v0, s[4:5]
	v_fma_f32 v196, v2, v195, v3
	v_pk_mul_f32 v[0:1], v[0:1], v[2:3]
	s_waitcnt lgkmcnt(0)
	v_fma_f32 v197, v4, v196, v5
	v_cndmask_b32_e64 v8, v8, v0, s[6:7]
	v_pk_mul_f32 v[4:5], v[0:1], v[4:5]
	ds_read2_b64 v[0:3], v89 offset0:128 offset1:144
	v_cndmask_b32_e64 v182, v8, v4, s[8:9]
	v_fma_f32 v198, v6, v197, v7
	v_pk_mul_f32 v[4:5], v[4:5], v[6:7]
	s_waitcnt lgkmcnt(0)
	v_fma_f32 v200, v0, v198, v1
	v_cndmask_b32_e64 v8, v79, v4, s[10:11]
	v_pk_mul_f32 v[0:1], v[4:5], v[0:1]
	ds_read2_b64 v[4:7], v89 offset0:160 offset1:176
	v_cndmask_b32_e64 v8, v8, v0, s[4:5]
	v_fma_f32 v201, v2, v200, v3
	v_pk_mul_f32 v[0:1], v[0:1], v[2:3]
	s_waitcnt lgkmcnt(0)
	v_fma_f32 v204, v4, v201, v5
	v_cndmask_b32_e64 v8, v8, v0, s[6:7]
	v_pk_mul_f32 v[4:5], v[0:1], v[4:5]
	ds_read2_b64 v[0:3], v89 offset0:192 offset1:208
	v_cndmask_b32_e64 v191, v8, v4, s[8:9]
	v_fma_f32 v205, v6, v204, v7
	v_pk_mul_f32 v[4:5], v[4:5], v[6:7]
	s_waitcnt lgkmcnt(0)
	v_fma_f32 v206, v0, v205, v1
	v_cndmask_b32_e64 v6, v77, v4, s[10:11]
	v_pk_mul_f32 v[0:1], v[4:5], v[0:1]
	v_fma_f32 v207, v2, v206, v3
	v_cndmask_b32_e64 v4, v6, v0, s[4:5]
	v_pk_mul_f32 v[0:1], v[0:1], v[2:3]
	s_nop 0
	v_cndmask_b32_e64 v77, v4, v0, s[6:7]
	v_pk_mul_f32 v[0:1], v[0:1], v[162:163]
	v_fmac_f32_e32 v163, v162, v207
	v_cndmask_b32_e64 v199, v77, v0, s[8:9]
	s_and_saveexec_b64 s[60:61], s[10:11]
	s_cbranch_execz .LBB0_230
	ds_read_b64 v[2:3], v59 offset:3968
	v_mov_b32_e32 v181, v178
	s_waitcnt lgkmcnt(0)
	v_pk_mul_f32 v[0:1], v[0:1], v[2:3]
	v_fmac_f32_e32 v3, v2, v163
	v_mov_b32_e32 v1, v3
	global_store_dwordx2 v[56:57], v[0:1], off
.LBB0_230:
	s_or_b64 exec, exec, s[60:61]
	v_mul_u32_u24_e32 v4, 0x110, v164
	s_or_b32 s60, s38, 0x1000
	s_mov_b32 s61, s39
	v_lshl_add_u64 v[0:1], v[48:49], 0, s[60:61]
	s_or_b32 s60, s38, 0x1800
	v_lshlrev_b64 v[0:1], 8, v[0:1]
	v_lshl_add_u64 v[12:13], v[48:49], 0, s[60:61]
	v_lshl_add_u64 v[176:177], v[160:161], 0, v[0:1]
	v_lshlrev_b64 v[12:13], 8, v[12:13]
	s_waitcnt vmcnt(1)
	v_mov_b64_e32 v[0:1], v[208:209]
	v_mov_b64_e32 v[2:3], v[210:211]
	v_add_u32_e32 v79, v165, v4
	v_lshl_add_u64 v[160:161], v[160:161], 0, v[12:13]
	ds_read_b128 v[4:7], v79
	ds_read_b128 v[8:11], v79 offset:4352
	v_mov_b64_e32 v[12:13], v[216:217]
	v_mov_b64_e32 v[14:15], v[218:219]
	v_mov_b64_e32 v[20:21], v[212:213]
	v_mov_b64_e32 v[22:23], v[214:215]
	v_mov_b64_e32 v[24:25], v[220:221]
	v_mov_b64_e32 v[26:27], v[222:223]
	ds_read_b128 v[32:35], v79 offset:8704
	ds_read_b128 v[36:39], v79 offset:13056
	ds_read_b128 v[164:167], v79 offset:17408
	ds_read_b128 v[168:171], v79 offset:21760
	ds_read_b128 v[212:215], v79 offset:26112
	ds_read_b128 v[216:219], v79 offset:30464
	s_waitcnt vmcnt(7) lgkmcnt(7)
	v_mfma_f32_16x16x32_bf16 v[16:19], v[4:7], v[0:3], 0
	s_waitcnt vmcnt(5)
	v_mfma_f32_16x16x32_bf16 v[4:7], v[4:7], v[20:23], 0
	s_waitcnt lgkmcnt(6)
	v_mfma_f32_16x16x32_bf16 v[28:31], v[8:11], v[0:3], 0
	v_mfma_f32_16x16x32_bf16 v[8:11], v[8:11], v[20:23], 0
	s_waitcnt lgkmcnt(5)
	v_mfma_f32_16x16x32_bf16 v[40:43], v[32:35], v[0:3], 0
	v_mfma_f32_16x16x32_bf16 v[32:35], v[32:35], v[20:23], 0
	s_waitcnt lgkmcnt(4)
; DI void lru_tile(const Params& p, unsigned char* shm, int c, int nb, const LruPar par) {
;     ...
;         for (int s = 0; s < 4; ++s)
; #pragma unroll
;             for (int gt = 0; gt < 2; ++gt) bfr[s][gt] = *(const bf16x8*)(LWT + ((size_t)((d * 2 + gt) * 16 + nb) * 128 + chl) * 128 + s * 32 + q * 8);
; #pragma unroll
;         for (int s = 0; s < 4; ++s) {
; #pragma unroll
;             for (int rt = 0; rt < 8; ++rt) {
;                 const bf16x8 af = *(const bf16x8*)(UB + (rt * 16 + col) * LDU + s * 32 + q * 8);
; #pragma unroll
;                 for (int gt = 0; gt < 2; ++gt) acc[gt][rt] = __builtin_amdgcn_mfma_f32_16x16x32_bf16(af, bfr[s][gt], acc[gt][rt], 0, 0, 0);
;             }
;             __builtin_amdgcn_sched_barrier(0);
;         }
	v_mfma_f32_16x16x32_bf16 v[44:47], v[36:39], v[0:3], 0
	v_mfma_f32_16x16x32_bf16 v[36:39], v[36:39], v[20:23], 0
	s_waitcnt lgkmcnt(3)
	v_mfma_f32_16x16x32_bf16 v[172:175], v[164:167], v[0:3], 0
	v_mfma_f32_16x16x32_bf16 v[164:167], v[164:167], v[20:23], 0
	s_waitcnt lgkmcnt(2)
	v_mfma_f32_16x16x32_bf16 v[208:211], v[168:171], v[0:3], 0
	v_mfma_f32_16x16x32_bf16 v[168:171], v[168:171], v[20:23], 0
	s_waitcnt lgkmcnt(1)
	v_mfma_f32_16x16x32_bf16 v[220:223], v[212:215], v[0:3], 0
	v_mfma_f32_16x16x32_bf16 v[212:215], v[212:215], v[20:23], 0
	s_waitcnt lgkmcnt(0)
	v_mfma_f32_16x16x32_bf16 v[0:3], v[216:219], v[0:3], 0
	v_mfma_f32_16x16x32_bf16 v[20:23], v[216:219], v[20:23], 0
	ds_read_b128 v[216:219], v79 offset:64
	ds_read_b128 v[240:243], v79 offset:4416
	s_waitcnt lgkmcnt(1)
	v_mfma_f32_16x16x32_bf16 v[16:19], v[216:219], v[12:15], v[16:19]
	s_waitcnt vmcnt(4)
	v_mfma_f32_16x16x32_bf16 v[4:7], v[216:219], v[24:27], v[4:7]
	s_waitcnt lgkmcnt(0)
	v_mfma_f32_16x16x32_bf16 v[28:31], v[240:243], v[12:15], v[28:31]
	v_mfma_f32_16x16x32_bf16 v[8:11], v[240:243], v[24:27], v[8:11]
	ds_read_b128 v[216:219], v79 offset:8768
	ds_read_b128 v[240:243], v79 offset:13120
	s_waitcnt lgkmcnt(1)
	v_mfma_f32_16x16x32_bf16 v[40:43], v[216:219], v[12:15], v[40:43]
	v_mfma_f32_16x16x32_bf16 v[32:35], v[216:219], v[24:27], v[32:35]
	s_waitcnt lgkmcnt(0)
	v_mfma_f32_16x16x32_bf16 v[44:47], v[240:243], v[12:15], v[44:47]
	v_mfma_f32_16x16x32_bf16 v[36:39], v[240:243], v[24:27], v[36:39]
	ds_read_b128 v[216:219], v79 offset:17472
	ds_read_b128 v[240:243], v79 offset:21824
	s_waitcnt lgkmcnt(1)
	v_mfma_f32_16x16x32_bf16 v[172:175], v[216:219], v[12:15], v[172:175]
	v_mfma_f32_16x16x32_bf16 v[164:167], v[216:219], v[24:27], v[164:167]
	s_waitcnt lgkmcnt(0)
	v_mfma_f32_16x16x32_bf16 v[208:211], v[240:243], v[12:15], v[208:211]
	v_mfma_f32_16x16x32_bf16 v[168:171], v[240:243], v[24:27], v[168:171]
	ds_read_b128 v[216:219], v79 offset:26176
	ds_read_b128 v[240:243], v79 offset:30528
	s_waitcnt lgkmcnt(1)
	v_mfma_f32_16x16x32_bf16 v[220:223], v[216:219], v[12:15], v[220:223]
	v_mfma_f32_16x16x32_bf16 v[212:215], v[216:219], v[24:27], v[212:215]
	s_waitcnt lgkmcnt(0)
	v_mfma_f32_16x16x32_bf16 v[0:3], v[240:243], v[12:15], v[0:3]
	v_mfma_f32_16x16x32_bf16 v[12:15], v[240:243], v[24:27], v[20:23]
	s_nop 2
	ds_read_b128 v[20:23], v79 offset:128
	ds_read_b128 v[24:27], v79 offset:4480
	s_waitcnt vmcnt(3) lgkmcnt(1)
	v_mfma_f32_16x16x32_bf16 v[16:19], v[20:23], v[224:227], v[16:19]
	s_waitcnt vmcnt(1)
	v_mfma_f32_16x16x32_bf16 v[4:7], v[20:23], v[232:235], v[4:7]
	s_waitcnt lgkmcnt(0)
	v_mfma_f32_16x16x32_bf16 v[20:23], v[24:27], v[224:227], v[28:31]
	v_mfma_f32_16x16x32_bf16 v[8:11], v[24:27], v[232:235], v[8:11]
	ds_read_b128 v[24:27], v79 offset:8832
	s_nop 0
	ds_read_b128 v[28:31], v79 offset:13184
	s_waitcnt lgkmcnt(1)
	v_mfma_f32_16x16x32_bf16 v[40:43], v[24:27], v[224:227], v[40:43]
	v_mfma_f32_16x16x32_bf16 v[24:27], v[24:27], v[232:235], v[32:35]
	s_waitcnt lgkmcnt(0)
	v_mfma_f32_16x16x32_bf16 v[32:35], v[28:31], v[224:227], v[44:47]
	v_mfma_f32_16x16x32_bf16 v[28:31], v[28:31], v[232:235], v[36:39]
	s_nop 2
	ds_read_b128 v[36:39], v79 offset:17536
	ds_read_b128 v[44:47], v79 offset:21888
	s_waitcnt lgkmcnt(1)
	v_mfma_f32_16x16x32_bf16 v[172:175], v[36:39], v[224:227], v[172:175]
	v_mfma_f32_16x16x32_bf16 v[164:167], v[36:39], v[232:235], v[164:167]
	s_waitcnt lgkmcnt(0)
	v_mfma_f32_16x16x32_bf16 v[208:211], v[44:47], v[224:227], v[208:211]
	v_mfma_f32_16x16x32_bf16 v[168:171], v[44:47], v[232:235], v[168:171]
	ds_read_b128 v[36:39], v79 offset:26240
	ds_read_b128 v[44:47], v79 offset:30592
	s_waitcnt lgkmcnt(1)
	v_mfma_f32_16x16x32_bf16 v[216:219], v[36:39], v[224:227], v[220:223]
	v_mfma_f32_16x16x32_bf16 v[212:215], v[36:39], v[232:235], v[212:215]
	s_waitcnt lgkmcnt(0)
	v_mfma_f32_16x16x32_bf16 v[0:3], v[44:47], v[224:227], v[0:3]
	v_mfma_f32_16x16x32_bf16 v[220:223], v[44:47], v[232:235], v[12:15]
	s_nop 2
	ds_read_b128 v[12:15], v79 offset:192
	ds_read_b128 v[36:39], v79 offset:4544
	s_waitcnt vmcnt(0) lgkmcnt(1)
	global_load_dword v252, v[248:249], off offset:-1024
	global_load_dword v253, v[248:249], off offset:-512
	global_load_dword v254, v[248:249], off
	global_load_dword v255, v[248:249], off offset:512
	global_load_dword v252, v[248:249], off offset:1024
	global_load_dword v253, v[248:249], off offset:1536
	global_load_dword v254, v[248:249], off offset:2048
	v_mfma_f32_16x16x32_bf16 v[232:235], v[12:15], v[236:239], v[4:7]
	s_waitcnt lgkmcnt(0)
	v_mfma_f32_16x16x32_bf16 v[244:247], v[36:39], v[236:239], v[8:11]
	s_nop 0
	ds_read_b128 v[4:7], v79 offset:8896
	s_nop 0
	ds_read_b128 v[8:11], v79 offset:13248
	v_mfma_f32_16x16x32_bf16 v[240:243], v[36:39], v[228:231], v[20:23]
	s_waitcnt lgkmcnt(1)
	v_mfma_f32_16x16x32_bf16 v[44:47], v[4:7], v[228:231], v[40:43]
	v_mfma_f32_16x16x32_bf16 v[40:43], v[4:7], v[236:239], v[24:27]
	s_waitcnt lgkmcnt(0)
	v_mfma_f32_16x16x32_bf16 v[36:39], v[8:11], v[228:231], v[32:35]
	v_mfma_f32_16x16x32_bf16 v[32:35], v[8:11], v[236:239], v[28:31]
	ds_read_b128 v[4:7], v79 offset:17600
	ds_read_b128 v[8:11], v79 offset:21952
	s_waitcnt lgkmcnt(1)
	v_mfma_f32_16x16x32_bf16 v[28:31], v[4:7], v[228:231], v[172:175]
	v_mfma_f32_16x16x32_bf16 v[24:27], v[4:7], v[236:239], v[164:167]
	ds_read_b128 v[4:7], v79 offset:26304
	s_nop 1
	ds_read_b128 v[164:167], v79 offset:30656
	v_mfma_f32_16x16x32_bf16 v[224:227], v[12:15], v[228:231], v[16:19]
	s_waitcnt lgkmcnt(2)
	v_mfma_f32_16x16x32_bf16 v[20:23], v[8:11], v[228:231], v[208:211]
	v_mfma_f32_16x16x32_bf16 v[16:19], v[8:11], v[236:239], v[168:171]
	s_waitcnt lgkmcnt(1)
; DI float bf2f(unsigned short b) { return __uint_as_float(((unsigned)b) << 16); }
; DI void lru_tile(const Params& p, unsigned char* shm, int c, int nb, const LruPar par) {
;     ...
;         for (int s = 0; s < 4; ++s) {
; #pragma unroll
;             for (int rt = 0; rt < 8; ++rt) {
;                 const bf16x8 af = *(const bf16x8*)(UB + (rt * 16 + col) * LDU + s * 32 + q * 8);
; #pragma unroll
;                 for (int gt = 0; gt < 2; ++gt) acc[gt][rt] = __builtin_amdgcn_mfma_f32_16x16x32_bf16(af, bfr[s][gt], acc[gt][rt], 0, 0, 0);
;             }
;             __builtin_amdgcn_sched_barrier(0);
;         }
;         const f32x2 nl2 = {-LOG2E, -LOG2E}, nbr2 = {par.nbr[d], par.nbr[d]}, nbi2 = {par.nbi[d], par.nbi[d]}, cd2 = {par.cdec[d], par.cdec[d]}, one2 = {1.f, 1.f};
;         float hl[8][4], pc[8][4];
; #pragma unroll
;         for (int rt = 0; rt < 8; ++rt) {
;             float av[4], bv[4];
; #pragma unroll
;             for (int jp = 0; jp < 2; ++jp) {
;                 const f32x2 xr = {acc[0][rt][2 * jp], acc[0][rt][2 * jp + 1]}, xi = {acc[1][rt][2 * jp], acc[1][rt][2 * jp + 1]};
;                 f32x2 er = xr * nl2 + nbr2, ei = xi * nl2 + nbi2;
;                 er = (f32x2){ex2(er[0]), ex2(er[1])} + one2; ei = (f32x2){ex2(ei[0]), ex2(ei[1])} + one2;
;                 const f32x2 r = {rcpf_(er[0]), rcpf_(er[1])}, ig = {rcpf_(ei[0]), rcpf_(ei[1])};
;                 const f32x2 la = r * cd2;
;                 const f32x2 a = {ex2(la[0]), ex2(la[1])};
;                 const f32x2 om = one2 - a * a;
;                 const f32x2 sc = {__builtin_amdgcn_sqrtf(om[0]), __builtin_amdgcn_sqrtf(om[1])};
;                 const f32x2 u2 = {bf2f(UB[(rt * 16 + 4 * q + 2 * jp) * LDU + chl]), bf2f(UB[(rt * 16 + 4 * q + 2 * jp + 1) * LDU + chl])};
;                 const f32x2 b2 = sc * ig * u2;
;                 av[2 * jp] = a[0]; av[2 * jp + 1] = a[1]; bv[2 * jp] = b2[0]; bv[2 * jp + 1] = b2[1];
;             }
;             float h = 0.f, P = 1.f;
;             if (d == 0) {
; #pragma unroll
;                 for (int j = 0; j < 4; ++j) { h = fmaf(av[j], h, bv[j]); P *= av[j]; hl[rt][j] = h; pc[rt][j] = P; }
;             } else {
; #pragma unroll
;                 for (int j = 3; j >= 0; --j) { h = fmaf(av[j], h, bv[j]); P *= av[j]; hl[rt][j] = h; pc[rt][j] = P; }
;             }
;             AG[(rt * 4 + q) * 16 + col] = (f32x2){P, h};
	v_mfma_f32_16x16x32_bf16 v[12:15], v[4:7], v[228:231], v[216:219]
	v_mfma_f32_16x16x32_bf16 v[8:11], v[4:7], v[236:239], v[212:215]
	s_waitcnt lgkmcnt(0)
	v_mfma_f32_16x16x32_bf16 v[4:7], v[164:167], v[228:231], v[0:3]
	v_mfma_f32_16x16x32_bf16 v[0:3], v[164:167], v[236:239], v[220:223]
	v_fma_f32 v160, -v226, s50, v83
	v_fma_f32 v161, -v227, s50, v83
	v_pk_fma_f32 v[164:165], v[234:235], s[50:51], v[86:87] op_sel:[0,0,1] op_sel_hi:[1,0,1] neg_lo:[1,0,0] neg_hi:[1,0,0]
	v_exp_f32_e32 v160, v160
	v_exp_f32_e32 v161, v161
	v_exp_f32_e32 v164, v164
	v_exp_f32_e32 v165, v165
	v_pk_fma_f32 v[168:169], v[224:225], s[50:51], v[82:83] op_sel:[0,0,1] op_sel_hi:[1,0,1] neg_lo:[1,0,0] neg_hi:[1,0,0]
	v_pk_add_f32 v[160:161], v[160:161], 1.0 op_sel_hi:[1,0]
	v_exp_f32_e32 v168, v168
	v_rcp_f32_e32 v160, v160
	v_rcp_f32_e32 v161, v161
	v_pk_add_f32 v[164:165], v[164:165], 1.0 op_sel_hi:[1,0]
	v_exp_f32_e32 v169, v169
	v_rcp_f32_e32 v164, v164
	v_pk_mul_f32 v[160:161], v[92:93], v[160:161] op_sel:[1,0]
	v_rcp_f32_e32 v165, v165
	v_exp_f32_e32 v161, v161
	v_exp_f32_e32 v160, v160
	ds_read_u16 v49, v68 offset:544
	ds_read_u16 v79, v97 offset:816
	ds_read_u16 v81, v97 offset:272
	ds_read_u16 v85, v68
	v_pk_fma_f32 v[166:167], v[160:161], v[160:161], 1.0 op_sel_hi:[1,1,0] neg_lo:[1,0,0] neg_hi:[1,0,0]
	s_nop 0
	v_sqrt_f32_e32 v166, v166
	v_sqrt_f32_e32 v167, v167
	s_nop 0
	v_pk_mul_f32 v[164:165], v[164:165], v[166:167]
	v_pk_add_f32 v[166:167], v[168:169], 1.0 op_sel_hi:[1,0]
	v_pk_fma_f32 v[168:169], v[232:233], s[50:51], v[86:87] op_sel:[0,0,1] op_sel_hi:[1,0,1] neg_lo:[1,0,0] neg_hi:[1,0,0]
	v_rcp_f32_e32 v166, v166
	v_rcp_f32_e32 v167, v167
	v_exp_f32_e32 v168, v168
	v_exp_f32_e32 v169, v169
	v_pk_mul_f32 v[166:167], v[92:93], v[166:167] op_sel:[1,0]
	s_nop 0
	v_exp_f32_e32 v170, v166
	v_exp_f32_e32 v171, v167
	v_pk_add_f32 v[166:167], v[168:169], 1.0 op_sel_hi:[1,0]
	s_nop 0
	v_rcp_f32_e32 v168, v166
	v_rcp_f32_e32 v169, v167
	v_pk_fma_f32 v[166:167], v[170:171], v[170:171], 1.0 op_sel_hi:[1,1,0] neg_lo:[1,0,0] neg_hi:[1,0,0]
	s_nop 0
	v_sqrt_f32_e32 v172, v166
	v_sqrt_f32_e32 v173, v167
	s_waitcnt lgkmcnt(3)
	v_lshlrev_b32_e32 v166, 16, v49
	s_waitcnt lgkmcnt(2)
	v_lshlrev_b32_e32 v167, 16, v79
	v_pk_mul_f32 v[166:167], v[164:165], v[166:167]
	v_pk_mul_f32 v[164:165], v[168:169], v[172:173]
	s_waitcnt lgkmcnt(0)
	v_lshlrev_b32_e32 v168, 16, v85
	v_lshlrev_b32_e32 v169, 16, v81
	v_fma_f32 v167, 0, v161, v167
	v_pk_mul_f32 v[168:169], v[164:165], v[168:169]
	v_fmac_f32_e32 v166, v160, v167
	v_mul_f32_e32 v160, v161, v160
	v_fma_f32 v169, v171, v166, v169
	v_mul_f32_e32 v49, v171, v160
	v_fmac_f32_e32 v168, v170, v169
	v_mul_f32_e32 v170, v170, v49
	v_mov_b32_e32 v171, v168
	ds_write_b64 v61, v[170:171]
	v_pk_fma_f32 v[164:165], v[242:243], s[50:51], v[82:83] op_sel:[0,0,1] op_sel_hi:[1,0,1] neg_lo:[1,0,0] neg_hi:[1,0,0]
	v_pk_fma_f32 v[172:173], v[246:247], s[50:51], v[86:87] op_sel:[0,0,1] op_sel_hi:[1,0,1] neg_lo:[1,0,0] neg_hi:[1,0,0]
	v_exp_f32_e32 v164, v164
	v_exp_f32_e32 v165, v165
	v_exp_f32_e32 v172, v172
	v_exp_f32_e32 v173, v173
	v_pk_fma_f32 v[176:177], v[240:241], s[50:51], v[82:83] op_sel:[0,0,1] op_sel_hi:[1,0,1] neg_lo:[1,0,0] neg_hi:[1,0,0]
	v_pk_add_f32 v[164:165], v[164:165], 1.0 op_sel_hi:[1,0]
	v_exp_f32_e32 v176, v176
	v_rcp_f32_e32 v164, v164
	v_rcp_f32_e32 v165, v165
	v_pk_add_f32 v[172:173], v[172:173], 1.0 op_sel_hi:[1,0]
	v_exp_f32_e32 v177, v177
	v_rcp_f32_e32 v172, v172
	v_pk_mul_f32 v[164:165], v[92:93], v[164:165] op_sel:[1,0]
	v_rcp_f32_e32 v173, v173
	v_exp_f32_e32 v165, v165
	v_exp_f32_e32 v164, v164
	ds_read_u16 v79, v68 offset:4896
	ds_read_u16 v81, v97 offset:5168
	ds_read_u16 v85, v97 offset:4624
	ds_read_u16 v91, v68 offset:4352
	v_pk_fma_f32 v[174:175], v[164:165], v[164:165], 1.0 op_sel_hi:[1,1,0] neg_lo:[1,0,0] neg_hi:[1,0,0]
	s_nop 0
	v_sqrt_f32_e32 v174, v174
	v_sqrt_f32_e32 v175, v175
	s_waitcnt lgkmcnt(3)
	v_lshlrev_b32_e32 v208, 16, v79
	s_waitcnt lgkmcnt(2)
	v_lshlrev_b32_e32 v209, 16, v81
	v_pk_mul_f32 v[172:173], v[172:173], v[174:175]
	v_pk_add_f32 v[174:175], v[176:177], 1.0 op_sel_hi:[1,0]
	v_pk_fma_f32 v[176:177], v[244:245], s[50:51], v[86:87] op_sel:[0,0,1] op_sel_hi:[1,0,1] neg_lo:[1,0,0] neg_hi:[1,0,0]
	v_rcp_f32_e32 v174, v174
	v_rcp_f32_e32 v175, v175
	v_exp_f32_e32 v176, v176
	v_exp_f32_e32 v177, v177
	v_pk_mul_f32 v[172:173], v[172:173], v[208:209]
	v_pk_mul_f32 v[174:175], v[92:93], v[174:175] op_sel:[1,0]
	v_fma_f32 v173, 0, v165, v173
	v_exp_f32_e32 v210, v174
	v_exp_f32_e32 v211, v175
	v_pk_add_f32 v[174:175], v[176:177], 1.0 op_sel_hi:[1,0]
	v_fmac_f32_e32 v172, v164, v173
	v_rcp_f32_e32 v174, v174
	v_pk_fma_f32 v[176:177], v[210:211], v[210:211], 1.0 op_sel_hi:[1,1,0] neg_lo:[1,0,0] neg_hi:[1,0,0]
	v_rcp_f32_e32 v175, v175
	v_sqrt_f32_e32 v176, v176
	v_sqrt_f32_e32 v177, v177
	v_mul_f32_e32 v164, v165, v164
	v_mul_f32_e32 v208, v211, v164
	v_pk_mul_f32 v[174:175], v[174:175], v[176:177]
	s_waitcnt lgkmcnt(0)
; DI float bf2f(unsigned short b) { return __uint_as_float(((unsigned)b) << 16); }
; DI float ex2(float x) { return __builtin_amdgcn_exp2f(x); }
; DI float rcpf_(float x) { return __builtin_amdgcn_rcpf(x); }
; DI void lru_tile(const Params& p, unsigned char* shm, int c, int nb, const LruPar par) {
;     ...
;         const f32x2 nl2 = {-LOG2E, -LOG2E}, nbr2 = {par.nbr[d], par.nbr[d]}, nbi2 = {par.nbi[d], par.nbi[d]}, cd2 = {par.cdec[d], par.cdec[d]}, one2 = {1.f, 1.f};
;         float hl[8][4], pc[8][4];
; #pragma unroll
;         for (int rt = 0; rt < 8; ++rt) {
;             float av[4], bv[4];
; #pragma unroll
;             for (int jp = 0; jp < 2; ++jp) {
;                 const f32x2 xr = {acc[0][rt][2 * jp], acc[0][rt][2 * jp + 1]}, xi = {acc[1][rt][2 * jp], acc[1][rt][2 * jp + 1]};
;                 f32x2 er = xr * nl2 + nbr2, ei = xi * nl2 + nbi2;
;                 er = (f32x2){ex2(er[0]), ex2(er[1])} + one2; ei = (f32x2){ex2(ei[0]), ex2(ei[1])} + one2;
;                 const f32x2 r = {rcpf_(er[0]), rcpf_(er[1])}, ig = {rcpf_(ei[0]), rcpf_(ei[1])};
;                 const f32x2 la = r * cd2;
;                 const f32x2 a = {ex2(la[0]), ex2(la[1])};
;                 const f32x2 om = one2 - a * a;
;                 const f32x2 sc = {__builtin_amdgcn_sqrtf(om[0]), __builtin_amdgcn_sqrtf(om[1])};
;                 const f32x2 u2 = {bf2f(UB[(rt * 16 + 4 * q + 2 * jp) * LDU + chl]), bf2f(UB[(rt * 16 + 4 * q + 2 * jp + 1) * LDU + chl])};
;                 const f32x2 b2 = sc * ig * u2;
;                 av[2 * jp] = a[0]; av[2 * jp + 1] = a[1]; bv[2 * jp] = b2[0]; bv[2 * jp + 1] = b2[1];
;             }
;             float h = 0.f, P = 1.f;
;             if (d == 0) {
; #pragma unroll
;                 for (int j = 0; j < 4; ++j) { h = fmaf(av[j], h, bv[j]); P *= av[j]; hl[rt][j] = h; pc[rt][j] = P; }
;             } else {
; #pragma unroll
;                 for (int j = 3; j >= 0; --j) { h = fmaf(av[j], h, bv[j]); P *= av[j]; hl[rt][j] = h; pc[rt][j] = P; }
;             }
;             AG[(rt * 4 + q) * 16 + col] = (f32x2){P, h};
;             __builtin_amdgcn_sched_barrier(0);
	v_lshlrev_b32_e32 v176, 16, v91
	v_lshlrev_b32_e32 v177, 16, v85
	v_pk_mul_f32 v[174:175], v[174:175], v[176:177]
	v_mul_f32_e32 v176, v210, v208
	v_fma_f32 v175, v211, v172, v175
	v_fmac_f32_e32 v174, v210, v175
	v_mov_b32_e32 v177, v174
	ds_write_b64 v61, v[176:177] offset:512
	v_pk_fma_f32 v[46:47], v[46:47], s[50:51], v[82:83] op_sel:[0,0,1] op_sel_hi:[1,0,1] neg_lo:[1,0,0] neg_hi:[1,0,0]
	v_pk_fma_f32 v[42:43], v[42:43], s[50:51], v[86:87] op_sel:[0,0,1] op_sel_hi:[1,0,1] neg_lo:[1,0,0] neg_hi:[1,0,0]
	v_exp_f32_e32 v46, v46
	v_exp_f32_e32 v47, v47
	v_pk_fma_f32 v[44:45], v[44:45], s[50:51], v[82:83] op_sel:[0,0,1] op_sel_hi:[1,0,1] neg_lo:[1,0,0] neg_hi:[1,0,0]
	v_exp_f32_e32 v210, v42
	v_exp_f32_e32 v211, v43
	v_pk_add_f32 v[46:47], v[46:47], 1.0 op_sel_hi:[1,0]
	v_exp_f32_e32 v44, v44
	v_rcp_f32_e32 v46, v46
	v_rcp_f32_e32 v47, v47
	v_exp_f32_e32 v45, v45
	v_pk_fma_f32 v[40:41], v[40:41], s[50:51], v[86:87] op_sel:[0,0,1] op_sel_hi:[1,0,1] neg_lo:[1,0,0] neg_hi:[1,0,0]
	ds_read_u16 v79, v68 offset:9248
	ds_read_u16 v81, v97 offset:9520
	v_pk_mul_f32 v[42:43], v[92:93], v[46:47] op_sel:[1,0]
	v_pk_add_f32 v[44:45], v[44:45], 1.0 op_sel_hi:[1,0]
	v_exp_f32_e32 v43, v43
	v_exp_f32_e32 v42, v42
	v_pk_add_f32 v[46:47], v[210:211], 1.0 op_sel_hi:[1,0]
	v_rcp_f32_e32 v44, v44
	v_rcp_f32_e32 v45, v45
	v_pk_fma_f32 v[210:211], v[42:43], v[42:43], 1.0 op_sel_hi:[1,1,0] neg_lo:[1,0,0] neg_hi:[1,0,0]
	v_rcp_f32_e32 v46, v46
	v_rcp_f32_e32 v47, v47
	v_sqrt_f32_e32 v210, v210
	v_sqrt_f32_e32 v211, v211
	v_exp_f32_e32 v40, v40
	v_exp_f32_e32 v41, v41
	v_pk_mul_f32 v[44:45], v[92:93], v[44:45] op_sel:[1,0]
	v_pk_mul_f32 v[46:47], v[46:47], v[210:211]
	v_exp_f32_e32 v210, v44
	v_exp_f32_e32 v211, v45
	v_pk_add_f32 v[40:41], v[40:41], 1.0 op_sel_hi:[1,0]
	ds_read_u16 v85, v97 offset:8976
	ds_read_u16 v91, v68 offset:8704
	v_rcp_f32_e32 v44, v40
	v_rcp_f32_e32 v45, v41
	v_pk_fma_f32 v[40:41], v[210:211], v[210:211], 1.0 op_sel_hi:[1,1,0] neg_lo:[1,0,0] neg_hi:[1,0,0]
	s_nop 0
	v_sqrt_f32_e32 v212, v40
	v_sqrt_f32_e32 v213, v41
	s_waitcnt lgkmcnt(3)
	v_lshlrev_b32_e32 v40, 16, v79
	s_waitcnt lgkmcnt(2)
	v_lshlrev_b32_e32 v41, 16, v81
	v_pk_mul_f32 v[40:41], v[46:47], v[40:41]
	v_pk_mul_f32 v[44:45], v[44:45], v[212:213]
	s_waitcnt lgkmcnt(0)
	v_lshlrev_b32_e32 v46, 16, v91
	v_lshlrev_b32_e32 v47, 16, v85
	v_fma_f32 v41, 0, v43, v41
	v_pk_mul_f32 v[44:45], v[44:45], v[46:47]
	v_fmac_f32_e32 v40, v42, v41
	v_mul_f32_e32 v42, v43, v42
	v_fma_f32 v45, v211, v40, v45
	v_mul_f32_e32 v209, v211, v42
	v_fmac_f32_e32 v44, v210, v45
	v_mul_f32_e32 v46, v210, v209
	v_mov_b32_e32 v47, v44
	ds_write_b64 v61, v[46:47] offset:1024
	v_pk_fma_f32 v[38:39], v[38:39], s[50:51], v[82:83] op_sel:[0,0,1] op_sel_hi:[1,0,1] neg_lo:[1,0,0] neg_hi:[1,0,0]
	v_pk_fma_f32 v[36:37], v[36:37], s[50:51], v[82:83] op_sel:[0,0,1] op_sel_hi:[1,0,1] neg_lo:[1,0,0] neg_hi:[1,0,0]
	v_exp_f32_e32 v38, v38
	v_exp_f32_e32 v39, v39
	v_exp_f32_e32 v36, v36
	v_exp_f32_e32 v37, v37
	v_pk_fma_f32 v[34:35], v[34:35], s[50:51], v[86:87] op_sel:[0,0,1] op_sel_hi:[1,0,1] neg_lo:[1,0,0] neg_hi:[1,0,0]
	v_pk_add_f32 v[38:39], v[38:39], 1.0 op_sel_hi:[1,0]
	v_exp_f32_e32 v210, v34
	v_rcp_f32_e32 v38, v38
	v_rcp_f32_e32 v39, v39
	v_pk_add_f32 v[36:37], v[36:37], 1.0 op_sel_hi:[1,0]
	v_exp_f32_e32 v211, v35
	v_rcp_f32_e32 v36, v36
	v_pk_mul_f32 v[34:35], v[92:93], v[38:39] op_sel:[1,0]
	v_rcp_f32_e32 v37, v37
	v_exp_f32_e32 v35, v35
	v_exp_f32_e32 v34, v34
	v_pk_fma_f32 v[32:33], v[32:33], s[50:51], v[86:87] op_sel:[0,0,1] op_sel_hi:[1,0,1] neg_lo:[1,0,0] neg_hi:[1,0,0]
	v_pk_mul_f32 v[36:37], v[92:93], v[36:37] op_sel:[1,0]
	v_exp_f32_e32 v32, v32
	v_exp_f32_e32 v33, v33
	v_pk_add_f32 v[38:39], v[210:211], 1.0 op_sel_hi:[1,0]
	v_pk_fma_f32 v[210:211], v[34:35], v[34:35], 1.0 op_sel_hi:[1,1,0] neg_lo:[1,0,0] neg_hi:[1,0,0]
	v_exp_f32_e32 v212, v36
	v_exp_f32_e32 v213, v37
	v_rcp_f32_e32 v38, v38
	v_rcp_f32_e32 v39, v39
	v_sqrt_f32_e32 v210, v210
	v_sqrt_f32_e32 v211, v211
	ds_read_u16 v47, v68 offset:13600
	ds_read_u16 v79, v97 offset:13872
	v_pk_add_f32 v[32:33], v[32:33], 1.0 op_sel_hi:[1,0]
	ds_read_u16 v81, v97 offset:13328
	ds_read_u16 v85, v68 offset:13056
	v_rcp_f32_e32 v36, v32
	v_rcp_f32_e32 v37, v33
	v_pk_fma_f32 v[32:33], v[212:213], v[212:213], 1.0 op_sel_hi:[1,1,0] neg_lo:[1,0,0] neg_hi:[1,0,0]
	v_pk_mul_f32 v[38:39], v[38:39], v[210:211]
	v_sqrt_f32_e32 v210, v32
	v_sqrt_f32_e32 v211, v33
	s_waitcnt lgkmcnt(3)
	v_lshlrev_b32_e32 v32, 16, v47
	s_waitcnt lgkmcnt(2)
	v_lshlrev_b32_e32 v33, 16, v79
	v_pk_mul_f32 v[32:33], v[38:39], v[32:33]
	v_pk_mul_f32 v[36:37], v[36:37], v[210:211]
	s_waitcnt lgkmcnt(0)
; DI float bf2f(unsigned short b) { return __uint_as_float(((unsigned)b) << 16); }
; DI float ex2(float x) { return __builtin_amdgcn_exp2f(x); }
; DI float rcpf_(float x) { return __builtin_amdgcn_rcpf(x); }
; DI void lru_tile(const Params& p, unsigned char* shm, int c, int nb, const LruPar par) {
;     ...
;         const f32x2 nl2 = {-LOG2E, -LOG2E}, nbr2 = {par.nbr[d], par.nbr[d]}, nbi2 = {par.nbi[d], par.nbi[d]}, cd2 = {par.cdec[d], par.cdec[d]}, one2 = {1.f, 1.f};
;         float hl[8][4], pc[8][4];
; #pragma unroll
;         for (int rt = 0; rt < 8; ++rt) {
;             float av[4], bv[4];
; #pragma unroll
;             for (int jp = 0; jp < 2; ++jp) {
;                 const f32x2 xr = {acc[0][rt][2 * jp], acc[0][rt][2 * jp + 1]}, xi = {acc[1][rt][2 * jp], acc[1][rt][2 * jp + 1]};
;                 f32x2 er = xr * nl2 + nbr2, ei = xi * nl2 + nbi2;
;                 er = (f32x2){ex2(er[0]), ex2(er[1])} + one2; ei = (f32x2){ex2(ei[0]), ex2(ei[1])} + one2;
;                 const f32x2 r = {rcpf_(er[0]), rcpf_(er[1])}, ig = {rcpf_(ei[0]), rcpf_(ei[1])};
;                 const f32x2 la = r * cd2;
;                 const f32x2 a = {ex2(la[0]), ex2(la[1])};
;                 const f32x2 om = one2 - a * a;
;                 const f32x2 sc = {__builtin_amdgcn_sqrtf(om[0]), __builtin_amdgcn_sqrtf(om[1])};
;                 const f32x2 u2 = {bf2f(UB[(rt * 16 + 4 * q + 2 * jp) * LDU + chl]), bf2f(UB[(rt * 16 + 4 * q + 2 * jp + 1) * LDU + chl])};
;                 const f32x2 b2 = sc * ig * u2;
;                 av[2 * jp] = a[0]; av[2 * jp + 1] = a[1]; bv[2 * jp] = b2[0]; bv[2 * jp + 1] = b2[1];
;             }
;             float h = 0.f, P = 1.f;
;             if (d == 0) {
; #pragma unroll
;                 for (int j = 0; j < 4; ++j) { h = fmaf(av[j], h, bv[j]); P *= av[j]; hl[rt][j] = h; pc[rt][j] = P; }
;             } else {
; #pragma unroll
;                 for (int j = 3; j >= 0; --j) { h = fmaf(av[j], h, bv[j]); P *= av[j]; hl[rt][j] = h; pc[rt][j] = P; }
;             }
;             AG[(rt * 4 + q) * 16 + col] = (f32x2){P, h};
;             __builtin_amdgcn_sched_barrier(0);
	v_lshlrev_b32_e32 v38, 16, v85
	v_lshlrev_b32_e32 v39, 16, v81
	v_fma_f32 v33, 0, v35, v33
	v_pk_mul_f32 v[36:37], v[36:37], v[38:39]
	v_fmac_f32_e32 v32, v34, v33
	v_mul_f32_e32 v34, v35, v34
	v_fma_f32 v37, v213, v32, v37
	v_mul_f32_e32 v210, v213, v34
	v_fmac_f32_e32 v36, v212, v37
	v_mul_f32_e32 v38, v212, v210
	v_mov_b32_e32 v39, v36
	ds_write_b64 v61, v[38:39] offset:1536
	v_pk_fma_f32 v[30:31], v[30:31], s[50:51], v[82:83] op_sel:[0,0,1] op_sel_hi:[1,0,1] neg_lo:[1,0,0] neg_hi:[1,0,0]
	v_pk_fma_f32 v[26:27], v[26:27], s[50:51], v[86:87] op_sel:[0,0,1] op_sel_hi:[1,0,1] neg_lo:[1,0,0] neg_hi:[1,0,0]
	v_exp_f32_e32 v30, v30
	v_exp_f32_e32 v31, v31
	v_pk_fma_f32 v[28:29], v[28:29], s[50:51], v[82:83] op_sel:[0,0,1] op_sel_hi:[1,0,1] neg_lo:[1,0,0] neg_hi:[1,0,0]
	v_exp_f32_e32 v212, v26
	v_exp_f32_e32 v213, v27
	v_pk_add_f32 v[30:31], v[30:31], 1.0 op_sel_hi:[1,0]
	v_exp_f32_e32 v28, v28
	v_rcp_f32_e32 v30, v30
	v_rcp_f32_e32 v31, v31
	v_exp_f32_e32 v29, v29
	v_pk_fma_f32 v[24:25], v[24:25], s[50:51], v[86:87] op_sel:[0,0,1] op_sel_hi:[1,0,1] neg_lo:[1,0,0] neg_hi:[1,0,0]
	ds_read_u16 v39, v68 offset:17952
	ds_read_u16 v47, v97 offset:18224
	v_pk_mul_f32 v[26:27], v[92:93], v[30:31] op_sel:[1,0]
	v_pk_add_f32 v[28:29], v[28:29], 1.0 op_sel_hi:[1,0]
	v_exp_f32_e32 v27, v27
	v_exp_f32_e32 v26, v26
	v_pk_add_f32 v[30:31], v[212:213], 1.0 op_sel_hi:[1,0]
	v_rcp_f32_e32 v28, v28
	v_rcp_f32_e32 v29, v29
	v_pk_fma_f32 v[212:213], v[26:27], v[26:27], 1.0 op_sel_hi:[1,1,0] neg_lo:[1,0,0] neg_hi:[1,0,0]
	v_rcp_f32_e32 v30, v30
	v_rcp_f32_e32 v31, v31
	v_sqrt_f32_e32 v212, v212
	v_sqrt_f32_e32 v213, v213
	v_exp_f32_e32 v24, v24
	v_exp_f32_e32 v25, v25
	v_pk_mul_f32 v[28:29], v[92:93], v[28:29] op_sel:[1,0]
	v_pk_mul_f32 v[30:31], v[30:31], v[212:213]
	v_exp_f32_e32 v212, v28
	v_exp_f32_e32 v213, v29
	v_pk_add_f32 v[24:25], v[24:25], 1.0 op_sel_hi:[1,0]
	ds_read_u16 v79, v97 offset:17680
	ds_read_u16 v81, v68 offset:17408
	v_rcp_f32_e32 v28, v24
	v_rcp_f32_e32 v29, v25
	v_pk_fma_f32 v[24:25], v[212:213], v[212:213], 1.0 op_sel_hi:[1,1,0] neg_lo:[1,0,0] neg_hi:[1,0,0]
	s_nop 0
	v_sqrt_f32_e32 v214, v24
	v_sqrt_f32_e32 v215, v25
	s_waitcnt lgkmcnt(3)
	v_lshlrev_b32_e32 v24, 16, v39
	s_waitcnt lgkmcnt(2)
	v_lshlrev_b32_e32 v25, 16, v47
	v_pk_mul_f32 v[24:25], v[30:31], v[24:25]
	v_pk_mul_f32 v[28:29], v[28:29], v[214:215]
	s_waitcnt lgkmcnt(0)
	v_lshlrev_b32_e32 v30, 16, v81
	v_lshlrev_b32_e32 v31, 16, v79
	v_fma_f32 v25, 0, v27, v25
	v_pk_mul_f32 v[28:29], v[28:29], v[30:31]
	v_fmac_f32_e32 v24, v26, v25
	v_mul_f32_e32 v26, v27, v26
	v_fma_f32 v29, v213, v24, v29
	v_mul_f32_e32 v211, v213, v26
	v_fmac_f32_e32 v28, v212, v29
	v_mul_f32_e32 v30, v212, v211
	v_mov_b32_e32 v31, v28
	ds_write_b64 v61, v[30:31] offset:2048
	v_pk_fma_f32 v[22:23], v[22:23], s[50:51], v[82:83] op_sel:[0,0,1] op_sel_hi:[1,0,1] neg_lo:[1,0,0] neg_hi:[1,0,0]
	v_pk_fma_f32 v[20:21], v[20:21], s[50:51], v[82:83] op_sel:[0,0,1] op_sel_hi:[1,0,1] neg_lo:[1,0,0] neg_hi:[1,0,0]
	v_exp_f32_e32 v22, v22
	v_exp_f32_e32 v23, v23
	v_exp_f32_e32 v20, v20
	v_exp_f32_e32 v21, v21
	v_pk_fma_f32 v[18:19], v[18:19], s[50:51], v[86:87] op_sel:[0,0,1] op_sel_hi:[1,0,1] neg_lo:[1,0,0] neg_hi:[1,0,0]
	v_pk_add_f32 v[22:23], v[22:23], 1.0 op_sel_hi:[1,0]
	v_exp_f32_e32 v212, v18
	v_rcp_f32_e32 v22, v22
	v_rcp_f32_e32 v23, v23
	v_pk_add_f32 v[20:21], v[20:21], 1.0 op_sel_hi:[1,0]
	v_exp_f32_e32 v213, v19
	v_rcp_f32_e32 v20, v20
	v_pk_mul_f32 v[18:19], v[92:93], v[22:23] op_sel:[1,0]
	v_rcp_f32_e32 v21, v21
	v_exp_f32_e32 v19, v19
	v_exp_f32_e32 v18, v18
	v_pk_fma_f32 v[16:17], v[16:17], s[50:51], v[86:87] op_sel:[0,0,1] op_sel_hi:[1,0,1] neg_lo:[1,0,0] neg_hi:[1,0,0]
	v_pk_mul_f32 v[20:21], v[92:93], v[20:21] op_sel:[1,0]
	v_exp_f32_e32 v16, v16
	v_exp_f32_e32 v17, v17
	v_pk_add_f32 v[22:23], v[212:213], 1.0 op_sel_hi:[1,0]
	v_pk_fma_f32 v[212:213], v[18:19], v[18:19], 1.0 op_sel_hi:[1,1,0] neg_lo:[1,0,0] neg_hi:[1,0,0]
	v_exp_f32_e32 v214, v20
	v_exp_f32_e32 v215, v21
	v_rcp_f32_e32 v22, v22
	v_rcp_f32_e32 v23, v23
	v_sqrt_f32_e32 v212, v212
	v_sqrt_f32_e32 v213, v213
	ds_read_u16 v31, v68 offset:22304
	ds_read_u16 v39, v97 offset:22576
	v_pk_add_f32 v[16:17], v[16:17], 1.0 op_sel_hi:[1,0]
	ds_read_u16 v47, v97 offset:22032
	ds_read_u16 v79, v68 offset:21760
	v_rcp_f32_e32 v20, v16
	v_rcp_f32_e32 v21, v17
	v_pk_fma_f32 v[16:17], v[214:215], v[214:215], 1.0 op_sel_hi:[1,1,0] neg_lo:[1,0,0] neg_hi:[1,0,0]
	v_pk_mul_f32 v[22:23], v[22:23], v[212:213]
	v_sqrt_f32_e32 v212, v16
	v_sqrt_f32_e32 v213, v17
	s_waitcnt lgkmcnt(3)
	v_lshlrev_b32_e32 v16, 16, v31
	s_waitcnt lgkmcnt(2)
	v_lshlrev_b32_e32 v17, 16, v39
	v_pk_mul_f32 v[16:17], v[22:23], v[16:17]
	v_pk_mul_f32 v[20:21], v[20:21], v[212:213]
	s_waitcnt lgkmcnt(0)
; DI float bf2f(unsigned short b) { return __uint_as_float(((unsigned)b) << 16); }
; DI float ex2(float x) { return __builtin_amdgcn_exp2f(x); }
; DI float rcpf_(float x) { return __builtin_amdgcn_rcpf(x); }
; DI void lru_tile(const Params& p, unsigned char* shm, int c, int nb, const LruPar par) {
;     ...
;         for (int rt = 0; rt < 8; ++rt) {
;             float av[4], bv[4];
; #pragma unroll
;             for (int jp = 0; jp < 2; ++jp) {
;                 const f32x2 xr = {acc[0][rt][2 * jp], acc[0][rt][2 * jp + 1]}, xi = {acc[1][rt][2 * jp], acc[1][rt][2 * jp + 1]};
;                 f32x2 er = xr * nl2 + nbr2, ei = xi * nl2 + nbi2;
;                 er = (f32x2){ex2(er[0]), ex2(er[1])} + one2; ei = (f32x2){ex2(ei[0]), ex2(ei[1])} + one2;
;                 const f32x2 r = {rcpf_(er[0]), rcpf_(er[1])}, ig = {rcpf_(ei[0]), rcpf_(ei[1])};
;                 const f32x2 la = r * cd2;
;                 const f32x2 a = {ex2(la[0]), ex2(la[1])};
;                 const f32x2 om = one2 - a * a;
;                 const f32x2 sc = {__builtin_amdgcn_sqrtf(om[0]), __builtin_amdgcn_sqrtf(om[1])};
;                 const f32x2 u2 = {bf2f(UB[(rt * 16 + 4 * q + 2 * jp) * LDU + chl]), bf2f(UB[(rt * 16 + 4 * q + 2 * jp + 1) * LDU + chl])};
;                 const f32x2 b2 = sc * ig * u2;
;                 av[2 * jp] = a[0]; av[2 * jp + 1] = a[1]; bv[2 * jp] = b2[0]; bv[2 * jp + 1] = b2[1];
;             }
;             float h = 0.f, P = 1.f;
;             if (d == 0) {
; #pragma unroll
;                 for (int j = 0; j < 4; ++j) { h = fmaf(av[j], h, bv[j]); P *= av[j]; hl[rt][j] = h; pc[rt][j] = P; }
;             } else {
; #pragma unroll
;                 for (int j = 3; j >= 0; --j) { h = fmaf(av[j], h, bv[j]); P *= av[j]; hl[rt][j] = h; pc[rt][j] = P; }
;             }
;             AG[(rt * 4 + q) * 16 + col] = (f32x2){P, h};
;             __builtin_amdgcn_sched_barrier(0);
;         }
;         asm volatile("s_waitcnt lgkmcnt(0)" ::: "memory");
;         float carry[8], pref[8]; float cin = 0.f, pa = 1.f;
; #pragma unroll
;         for (int gi = 0; gi < 32; ++gi) {
;             const int G = d == 0 ? gi : 31 - gi; const int rt = G >> 2, qq = G & 3;
;             const f32x2 ah = AG[G * 16 + col];
;             if (qq == q) { carry[rt] = cin; pref[rt] = pa; }
;             cin = fmaf(ah[0], cin, ah[1]); pa *= ah[0];
;         }
	v_lshlrev_b32_e32 v22, 16, v79
	v_lshlrev_b32_e32 v23, 16, v47
	v_fma_f32 v17, 0, v19, v17
	v_pk_mul_f32 v[20:21], v[20:21], v[22:23]
	v_fmac_f32_e32 v16, v18, v17
	v_mul_f32_e32 v18, v19, v18
	v_fma_f32 v21, v215, v16, v21
	v_mul_f32_e32 v212, v215, v18
	v_fmac_f32_e32 v20, v214, v21
	v_mul_f32_e32 v22, v214, v212
	v_mov_b32_e32 v23, v20
	ds_write_b64 v61, v[22:23] offset:2560
	v_pk_fma_f32 v[14:15], v[14:15], s[50:51], v[82:83] op_sel:[0,0,1] op_sel_hi:[1,0,1] neg_lo:[1,0,0] neg_hi:[1,0,0]
	v_pk_fma_f32 v[10:11], v[10:11], s[50:51], v[86:87] op_sel:[0,0,1] op_sel_hi:[1,0,1] neg_lo:[1,0,0] neg_hi:[1,0,0]
	v_exp_f32_e32 v14, v14
	v_exp_f32_e32 v15, v15
	v_pk_fma_f32 v[12:13], v[12:13], s[50:51], v[82:83] op_sel:[0,0,1] op_sel_hi:[1,0,1] neg_lo:[1,0,0] neg_hi:[1,0,0]
	v_exp_f32_e32 v214, v10
	v_exp_f32_e32 v215, v11
	v_pk_add_f32 v[14:15], v[14:15], 1.0 op_sel_hi:[1,0]
	v_exp_f32_e32 v12, v12
	v_rcp_f32_e32 v14, v14
	v_rcp_f32_e32 v15, v15
	v_exp_f32_e32 v13, v13
	v_pk_fma_f32 v[8:9], v[8:9], s[50:51], v[86:87] op_sel:[0,0,1] op_sel_hi:[1,0,1] neg_lo:[1,0,0] neg_hi:[1,0,0]
	ds_read_u16 v23, v68 offset:26656
	ds_read_u16 v31, v97 offset:26928
	v_pk_mul_f32 v[10:11], v[92:93], v[14:15] op_sel:[1,0]
	v_pk_add_f32 v[12:13], v[12:13], 1.0 op_sel_hi:[1,0]
	v_exp_f32_e32 v11, v11
	v_exp_f32_e32 v10, v10
	v_pk_add_f32 v[14:15], v[214:215], 1.0 op_sel_hi:[1,0]
	v_rcp_f32_e32 v12, v12
	v_rcp_f32_e32 v13, v13
	v_pk_fma_f32 v[214:215], v[10:11], v[10:11], 1.0 op_sel_hi:[1,1,0] neg_lo:[1,0,0] neg_hi:[1,0,0]
	v_rcp_f32_e32 v14, v14
	v_rcp_f32_e32 v15, v15
	v_sqrt_f32_e32 v214, v214
	v_sqrt_f32_e32 v215, v215
	v_exp_f32_e32 v8, v8
	v_exp_f32_e32 v9, v9
	v_pk_mul_f32 v[12:13], v[92:93], v[12:13] op_sel:[1,0]
	v_pk_mul_f32 v[14:15], v[14:15], v[214:215]
	v_exp_f32_e32 v214, v12
	v_exp_f32_e32 v215, v13
	v_pk_add_f32 v[8:9], v[8:9], 1.0 op_sel_hi:[1,0]
	ds_read_u16 v39, v97 offset:26384
	ds_read_u16 v47, v68 offset:26112
	v_rcp_f32_e32 v12, v8
	v_rcp_f32_e32 v13, v9
	v_pk_fma_f32 v[8:9], v[214:215], v[214:215], 1.0 op_sel_hi:[1,1,0] neg_lo:[1,0,0] neg_hi:[1,0,0]
	s_nop 0
	v_sqrt_f32_e32 v216, v8
	v_sqrt_f32_e32 v217, v9
	s_waitcnt lgkmcnt(3)
	v_lshlrev_b32_e32 v8, 16, v23
	s_waitcnt lgkmcnt(2)
	v_lshlrev_b32_e32 v9, 16, v31
	v_pk_mul_f32 v[8:9], v[14:15], v[8:9]
	v_pk_mul_f32 v[12:13], v[12:13], v[216:217]
	s_waitcnt lgkmcnt(0)
	v_lshlrev_b32_e32 v14, 16, v47
	v_lshlrev_b32_e32 v15, 16, v39
	v_fma_f32 v9, 0, v11, v9
	v_pk_mul_f32 v[12:13], v[12:13], v[14:15]
	v_fmac_f32_e32 v8, v10, v9
	v_mul_f32_e32 v10, v11, v10
	v_fma_f32 v13, v215, v8, v13
	v_mul_f32_e32 v213, v215, v10
	v_fmac_f32_e32 v12, v214, v13
	v_mul_f32_e32 v14, v214, v213
	v_mov_b32_e32 v15, v12
	ds_write_b64 v61, v[14:15] offset:3072
	v_pk_fma_f32 v[6:7], v[6:7], s[50:51], v[82:83] op_sel:[0,0,1] op_sel_hi:[1,0,1] neg_lo:[1,0,0] neg_hi:[1,0,0]
	v_pk_fma_f32 v[4:5], v[4:5], s[50:51], v[82:83] op_sel:[0,0,1] op_sel_hi:[1,0,1] neg_lo:[1,0,0] neg_hi:[1,0,0]
	v_exp_f32_e32 v6, v6
	v_exp_f32_e32 v7, v7
	v_exp_f32_e32 v4, v4
	v_exp_f32_e32 v5, v5
	v_pk_fma_f32 v[2:3], v[2:3], s[50:51], v[86:87] op_sel:[0,0,1] op_sel_hi:[1,0,1] neg_lo:[1,0,0] neg_hi:[1,0,0]
	v_pk_add_f32 v[6:7], v[6:7], 1.0 op_sel_hi:[1,0]
	v_exp_f32_e32 v214, v2
	v_rcp_f32_e32 v6, v6
	v_rcp_f32_e32 v7, v7
	v_pk_add_f32 v[4:5], v[4:5], 1.0 op_sel_hi:[1,0]
	v_exp_f32_e32 v215, v3
	v_rcp_f32_e32 v4, v4
	v_pk_mul_f32 v[2:3], v[92:93], v[6:7] op_sel:[1,0]
	v_rcp_f32_e32 v5, v5
	v_exp_f32_e32 v3, v3
	v_exp_f32_e32 v2, v2
	v_pk_fma_f32 v[0:1], v[0:1], s[50:51], v[86:87] op_sel:[0,0,1] op_sel_hi:[1,0,1] neg_lo:[1,0,0] neg_hi:[1,0,0]
	v_pk_mul_f32 v[4:5], v[92:93], v[4:5] op_sel:[1,0]
	v_exp_f32_e32 v0, v0
	v_exp_f32_e32 v1, v1
	v_pk_add_f32 v[6:7], v[214:215], 1.0 op_sel_hi:[1,0]
	v_pk_fma_f32 v[214:215], v[2:3], v[2:3], 1.0 op_sel_hi:[1,1,0] neg_lo:[1,0,0] neg_hi:[1,0,0]
	v_exp_f32_e32 v216, v4
	v_exp_f32_e32 v217, v5
	v_rcp_f32_e32 v6, v6
	v_rcp_f32_e32 v7, v7
	v_sqrt_f32_e32 v214, v214
	v_sqrt_f32_e32 v215, v215
	ds_read_u16 v15, v68 offset:31008
	ds_read_u16 v23, v97 offset:31280
	v_pk_add_f32 v[0:1], v[0:1], 1.0 op_sel_hi:[1,0]
	ds_read_u16 v31, v97 offset:30736
	ds_read_u16 v39, v68 offset:30464
	v_rcp_f32_e32 v4, v0
	v_rcp_f32_e32 v5, v1
	v_pk_fma_f32 v[0:1], v[216:217], v[216:217], 1.0 op_sel_hi:[1,1,0] neg_lo:[1,0,0] neg_hi:[1,0,0]
	v_pk_mul_f32 v[6:7], v[6:7], v[214:215]
	v_sqrt_f32_e32 v214, v0
	v_sqrt_f32_e32 v215, v1
	s_waitcnt lgkmcnt(3)
	v_lshlrev_b32_e32 v0, 16, v15
	s_waitcnt lgkmcnt(2)
	v_lshlrev_b32_e32 v1, 16, v23
	v_pk_mul_f32 v[0:1], v[6:7], v[0:1]
	v_pk_mul_f32 v[4:5], v[4:5], v[214:215]
	s_waitcnt lgkmcnt(0)
	v_lshlrev_b32_e32 v6, 16, v39
	v_lshlrev_b32_e32 v7, 16, v31
	v_fma_f32 v1, 0, v3, v1
	v_pk_mul_f32 v[4:5], v[4:5], v[6:7]
	v_fmac_f32_e32 v0, v2, v1
	v_mul_f32_e32 v2, v3, v2
	v_fma_f32 v5, v217, v0, v5
	v_mul_f32_e32 v214, v217, v2
	v_fmac_f32_e32 v4, v216, v5
	v_mul_f32_e32 v6, v216, v214
	v_mov_b32_e32 v7, v4
	ds_write_b64 v61, v[6:7] offset:3584
	s_waitcnt lgkmcnt(0)
	ds_read_b64 v[220:221], v59 offset:3968
	ds_read2_b64 v[216:219], v89 offset0:208 offset1:224
	v_cndmask_b32_e64 v15, v77, 1.0, s[8:9]
	v_add_u32_e32 v85, 0x400, v59
	s_waitcnt lgkmcnt(1)
	v_fma_f32 v7, 0, v220, v221
	v_cndmask_b32_e64 v23, v15, v220, s[6:7]
	s_waitcnt lgkmcnt(0)
; DI void lru_tile(const Params& p, unsigned char* shm, int c, int nb, const LruPar par) {
;     ...
;         float carry[8], pref[8]; float cin = 0.f, pa = 1.f;
; #pragma unroll
;         for (int gi = 0; gi < 32; ++gi) {
;             const int G = d == 0 ? gi : 31 - gi; const int rt = G >> 2, qq = G & 3;
;             const f32x2 ah = AG[G * 16 + col];
;             if (qq == q) { carry[rt] = cin; pref[rt] = pa; }
;             cin = fmaf(ah[0], cin, ah[1]); pa *= ah[0];
;         }
;         if (q == 0) AGG[((size_t)d * 128 + c) * 2048 + chg] = (f32x2){pa, cin};
	v_pk_mul_f32 v[222:223], v[220:221], v[218:219]
	v_fma_f32 v15, v218, v7, v219
	ds_read2_b64 v[218:221], v89 offset0:176 offset1:192
	v_cndmask_b32_e64 v31, v23, v222, s[4:5]
	v_fma_f32 v23, v216, v15, v217
	v_pk_mul_f32 v[216:217], v[222:223], v[216:217]
	s_waitcnt lgkmcnt(0)
	v_fma_f32 v39, v220, v23, v221
	v_cndmask_b32_e64 v77, v31, v216, s[10:11]
	v_pk_mul_f32 v[216:217], v[216:217], v[220:221]
	ds_read2_b64 v[220:223], v89 offset0:144 offset1:160
	v_cndmask_b32_e64 v31, v191, v216, s[8:9]
	v_fma_f32 v47, v218, v39, v219
	v_pk_mul_f32 v[216:217], v[216:217], v[218:219]
	s_waitcnt lgkmcnt(0)
	v_fma_f32 v61, v222, v47, v223
	v_cndmask_b32_e64 v31, v31, v216, s[6:7]
	v_pk_mul_f32 v[222:223], v[216:217], v[222:223]
	ds_read2_b64 v[216:219], v89 offset0:112 offset1:128
	v_cndmask_b32_e64 v31, v31, v222, s[4:5]
	v_fma_f32 v97, v220, v61, v221
	v_pk_mul_f32 v[220:221], v[222:223], v[220:221]
	s_waitcnt lgkmcnt(0)
	v_fma_f32 v171, v218, v97, v219
	v_cndmask_b32_e64 v79, v31, v220, s[10:11]
	v_pk_mul_f32 v[222:223], v[220:221], v[218:219]
	ds_read2_b64 v[218:221], v89 offset0:80 offset1:96
	v_fma_f32 v177, v216, v171, v217
	v_pk_mul_f32 v[216:217], v[222:223], v[216:217]
	v_cndmask_b32_e64 v31, v182, v222, s[8:9]
	v_cndmask_b32_e64 v31, v31, v216, s[6:7]
	s_waitcnt lgkmcnt(0)
	v_fma_f32 v215, v220, v177, v221
	v_pk_mul_f32 v[224:225], v[216:217], v[220:221]
	ds_read2_b64 v[220:223], v89 offset0:48 offset1:64
	v_fma_f32 v216, v218, v215, v219
	v_pk_mul_f32 v[218:219], v[224:225], v[218:219]
	v_cndmask_b32_e64 v31, v31, v224, s[4:5]
	v_cndmask_b32_e64 v81, v31, v218, s[10:11]
	s_waitcnt lgkmcnt(0)
	v_fma_f32 v217, v222, v216, v223
	v_pk_mul_f32 v[226:227], v[218:219], v[222:223]
	ds_read2_b64 v[222:225], v89 offset0:16 offset1:32
	v_fma_f32 v218, v220, v217, v221
	v_pk_mul_f32 v[220:221], v[226:227], v[220:221]
	v_cndmask_b32_e64 v31, v117, v226, s[8:9]
	v_cndmask_b32_e64 v31, v31, v220, s[6:7]
	s_waitcnt lgkmcnt(0)
	v_fma_f32 v219, v224, v218, v225
	v_pk_mul_f32 v[228:229], v[220:221], v[224:225]
	ds_read2_b64 v[224:227], v85 offset0:112 offset1:128
	v_fma_f32 v220, v222, v219, v223
	v_pk_mul_f32 v[222:223], v[228:229], v[222:223]
	v_cndmask_b32_e64 v31, v31, v228, s[4:5]
	v_cndmask_b32_e64 v85, v31, v222, s[10:11]
	s_waitcnt lgkmcnt(0)
	v_fma_f32 v221, v226, v220, v227
	v_pk_mul_f32 v[230:231], v[222:223], v[226:227]
	ds_read2_b64 v[226:229], v59 offset0:208 offset1:224
	v_fma_f32 v222, v224, v221, v225
	v_pk_mul_f32 v[224:225], v[230:231], v[224:225]
	v_cndmask_b32_e64 v31, v109, v230, s[8:9]
	v_cndmask_b32_e64 v31, v31, v224, s[6:7]
	s_waitcnt lgkmcnt(0)
	v_fma_f32 v223, v228, v222, v229
	v_pk_mul_f32 v[232:233], v[224:225], v[228:229]
	ds_read2_b64 v[228:231], v59 offset0:176 offset1:192
	v_fma_f32 v224, v226, v223, v227
	v_pk_mul_f32 v[226:227], v[232:233], v[226:227]
	v_cndmask_b32_e64 v31, v31, v232, s[4:5]
	v_cndmask_b32_e64 v89, v31, v226, s[10:11]
	s_waitcnt lgkmcnt(0)
	v_fma_f32 v225, v230, v224, v231
	v_pk_mul_f32 v[234:235], v[226:227], v[230:231]
	ds_read2_b64 v[230:233], v59 offset0:144 offset1:160
	v_fma_f32 v226, v228, v225, v229
	v_pk_mul_f32 v[228:229], v[234:235], v[228:229]
	v_cndmask_b32_e64 v31, v107, v234, s[8:9]
	v_cndmask_b32_e64 v31, v31, v228, s[6:7]
	s_waitcnt lgkmcnt(0)
	v_fma_f32 v227, v232, v226, v233
	v_pk_mul_f32 v[236:237], v[228:229], v[232:233]
	ds_read2_b64 v[232:235], v59 offset0:112 offset1:128
	v_fma_f32 v228, v230, v227, v231
	v_pk_mul_f32 v[230:231], v[236:237], v[230:231]
	v_cndmask_b32_e64 v31, v31, v236, s[4:5]
	v_cndmask_b32_e64 v91, v31, v230, s[10:11]
	s_waitcnt lgkmcnt(0)
	v_fma_f32 v229, v234, v228, v235
	v_pk_mul_f32 v[238:239], v[230:231], v[234:235]
	ds_read2_b64 v[234:237], v59 offset0:80 offset1:96
	v_fma_f32 v230, v232, v229, v233
	v_pk_mul_f32 v[232:233], v[238:239], v[232:233]
	v_cndmask_b32_e64 v31, v99, v238, s[8:9]
	v_cndmask_b32_e64 v31, v31, v232, s[6:7]
	s_waitcnt lgkmcnt(0)
	v_fma_f32 v231, v236, v230, v237
	v_pk_mul_f32 v[240:241], v[232:233], v[236:237]
	ds_read2_b64 v[236:239], v59 offset0:48 offset1:64
	v_fma_f32 v232, v234, v231, v235
	v_pk_mul_f32 v[234:235], v[240:241], v[234:235]
	v_cndmask_b32_e64 v31, v31, v240, s[4:5]
	v_cndmask_b32_e64 v162, v31, v234, s[10:11]
	s_waitcnt lgkmcnt(0)
	v_fma_f32 v233, v238, v232, v239
	v_pk_mul_f32 v[242:243], v[234:235], v[238:239]
	ds_read2_b64 v[238:241], v59 offset0:16 offset1:32
	v_cndmask_b32_e64 v31, v178, v242, s[8:9]
	v_pk_mul_f32 v[178:179], v[242:243], v[236:237]
	v_fma_f32 v234, v236, v233, v237
	v_cndmask_b32_e64 v31, v31, v178, s[6:7]
	v_cndmask_b32_e64 v180, v242, v178, s[6:7]
	s_waitcnt lgkmcnt(0)
	v_pk_mul_f32 v[178:179], v[178:179], v[240:241]
	v_fma_f32 v235, v240, v234, v241
	v_cndmask_b32_e64 v237, v31, v178, s[4:5]
	v_cndmask_b32_e64 v31, v180, v178, s[4:5]
	v_pk_mul_f32 v[178:179], v[178:179], v[238:239]
	v_fma_f32 v236, v238, v235, v239
	v_cndmask_b32_e64 v180, v237, v178, s[10:11]
	s_and_saveexec_b64 s[60:61], s[10:11]
	s_cbranch_execz .LBB0_211
	ds_read_b64 v[238:239], v59
	v_add_co_u32_e32 v56, vcc, 0x200000, v56
	v_mov_b32_e32 v31, v180
	s_nop 0
	v_addc_co_u32_e32 v57, vcc, 0, v57, vcc
	s_waitcnt lgkmcnt(0)
	v_pk_mul_f32 v[178:179], v[178:179], v[238:239]
	v_fmac_f32_e32 v239, v238, v236
	v_mov_b32_e32 v179, v239
	global_store_dwordx2 v[56:57], v[178:179], off
	s_branch .LBB0_211
